# down-sout-epilogue-gate-loads-issued-up-front
# baseline (speedup 1.0000x reference)
; #define PG8_STAGE(bufoff, gbase, hoff, imm) do { _Pragma("unroll") for (int _i = 0; _i < 2; ++_i) { \
;         asm volatile("s_mov_b32 m0, %0\n\ts_nop 0\n\tglobal_load_lds_dwordx4 %1, %2" \
;             :: "s"(lds0 + (unsigned)((bufoff) + _i * 8192)), "v"(voff0), "s"((const char*)(gbase) + (size_t)(hoff) + (size_t)(_i * 8192)) : "memory"); } } while (0)
; #define PG8_LDA(dst, b, h) do { _Pragma("unroll") for (int m = 0; m < 4; ++m) _Pragma("unroll") for (int k = 0; k < 2; ++k) dst[m][k] = *(const LAS bf16x8*)(lds + PG8_SA(b, h) + aoff + m * 2048 + k * 1024); } while (0)
; #define PG8_LDB(dst, b, h) do { _Pragma("unroll") for (int n = 0; n < 2; ++n) _Pragma("unroll") for (int k = 0; k < 2; ++k) dst[n][k] = *(const LAS bf16x8*)(lds + PG8_SB(b, h) + boff + n * 2048 + k * 1024); } while (0)
; #define PG8_MMA(ai, bj, At, Bt) do { __builtin_amdgcn_s_setprio(1); _Pragma("unroll") for (int m = 0; m < 4; ++m) _Pragma("unroll") for (int n = 0; n < 2; ++n) _Pragma("unroll") for (int k = 0; k < 2; ++k) \
;         acc[ai][bj][m][n] = __builtin_amdgcn_mfma_f32_16x16x32_bf16(Bt[n][k], At[m][k], acc[ai][bj][m][n], 0, 0, 0); __builtin_amdgcn_s_setprio(0); } while (0)
; #define PG8_WAIT_V(n) asm volatile("s_waitcnt vmcnt(" #n ")" ::: "memory")
; #define PG8_WAIT_L(n) asm volatile("s_waitcnt lgkmcnt(" #n ")" ::: "memory")
; #define PG8_BAR __builtin_amdgcn_s_barrier()
; #define PG8_SCHED __builtin_amdgcn_sched_barrier(0)
; template <class Epi>
; __device__ __forceinline__ void gemm_phase(LAS unsigned char* lds, const Gemm g, const StaticOrder& S, const Epi& E) {
;     ...
;             PG8_LDB(B0, 0, 0); PG8_SCHED; PG8_LDA(At, 0, 0); PG8_STAGE(PG8_SA(1, 1), aT + KS, hA, 0);
;             PG8_WAIT_L(8); PG8_BAR; PG8_WAIT_L(0); PG8_MMA(0, 0, At, B0); PG8_BAR; PG8_SCHED;
;             PG8_LDB(B1, 0, 1); PG8_STAGE(PG8_SB(0, 0), b2, 0, 0);
;             PG8_BAR; PG8_WAIT_L(0); PG8_MMA(0, 1, At, B1); PG8_BAR;
;             PG8_LDA(At, 0, 1); PG8_STAGE(PG8_SA(0, 0), a2, 0, 0);
;             PG8_BAR; PG8_WAIT_L(0); PG8_MMA(1, 0, At, B0); PG8_BAR; PG8_SCHED;
;             PG8_STAGE(PG8_SB(0, 1), b2, hB, 0);
;             PG8_WAIT_V(6); PG8_BAR; PG8_MMA(1, 1, At, B1); PG8_BAR;
.LBB0_610:
	s_add_u32 s62, s60, 0x8000
	v_add_u32_e32 v132, 0x10000, v236
	s_addc_u32 s63, s61, 0
	ds_read_b128 v[120:123], v132
	ds_read_b128 v[124:127], v132 offset:1024
	ds_read_b128 v[128:131], v132 offset:2048
	ds_read_b128 v[132:135], v132 offset:3072
	s_add_u32 s48, s60, 0x84000
	s_addc_u32 s49, s61, 0
	s_add_u32 s64, s60, 0x86000
	s_addc_u32 s65, s61, 0
	s_cmp_eq_u32 s71, 28
	s_cselect_b32 s61, s0, s63
	s_cselect_b32 s60, s1, s62
	ds_read_b128 v[136:139], v237
	ds_read_b128 v[140:143], v237 offset:1024
	ds_read_b128 v[152:155], v237 offset:2048
	ds_read_b128 v[156:159], v237 offset:3072
	ds_read_b128 v[160:163], v237 offset:4096
	ds_read_b128 v[164:167], v237 offset:5120
	ds_read_b128 v[168:171], v237 offset:6144
	ds_read_b128 v[172:175], v237 offset:7168
	s_mov_b32 m0, s67
	s_nop 0
	global_load_lds_dwordx4 v188, s[48:49]
	s_mov_b32 m0, s68
	s_nop 0
	global_load_lds_dwordx4 v188, s[64:65]
	s_waitcnt lgkmcnt(8)
	s_waitcnt vmcnt(10)
	s_barrier
	s_waitcnt lgkmcnt(7)
	v_mfma_f32_16x16x32_bf16 v[148:151], v[120:123], v[136:139], v[148:151]
	v_mfma_f32_16x16x32_bf16 v[144:147], v[128:131], v[136:139], v[144:147]
	s_waitcnt lgkmcnt(5)
	v_mfma_f32_16x16x32_bf16 v[108:111], v[120:123], v[152:155], v[108:111]
	v_mfma_f32_16x16x32_bf16 v[104:107], v[128:131], v[152:155], v[104:107]
	s_waitcnt lgkmcnt(3)
	v_mfma_f32_16x16x32_bf16 v[92:95], v[120:123], v[160:163], v[92:95]
	v_mfma_f32_16x16x32_bf16 v[88:91], v[128:131], v[160:163], v[88:91]
	s_waitcnt lgkmcnt(1)
	v_mfma_f32_16x16x32_bf16 v[76:79], v[120:123], v[168:171], v[76:79]
	v_mfma_f32_16x16x32_bf16 v[72:75], v[128:131], v[168:171], v[72:75]
	v_mfma_f32_16x16x32_bf16 v[148:151], v[124:127], v[140:143], v[148:151]
	v_mfma_f32_16x16x32_bf16 v[144:147], v[132:135], v[140:143], v[144:147]
	v_mfma_f32_16x16x32_bf16 v[108:111], v[124:127], v[156:159], v[108:111]
	v_mfma_f32_16x16x32_bf16 v[104:107], v[132:135], v[156:159], v[104:107]
	v_mfma_f32_16x16x32_bf16 v[92:95], v[124:127], v[164:167], v[92:95]
	v_mfma_f32_16x16x32_bf16 v[88:91], v[132:135], v[164:167], v[88:91]
	s_waitcnt lgkmcnt(0)
	v_mfma_f32_16x16x32_bf16 v[76:79], v[124:127], v[172:175], v[76:79]
	v_mfma_f32_16x16x32_bf16 v[72:75], v[132:135], v[172:175], v[72:75]
	s_barrier
	v_add_u32_e32 v200, 0x14000, v236
	ds_read_b128 v[176:179], v200
	ds_read_b128 v[180:183], v200 offset:1024
	ds_read_b128 v[184:187], v200 offset:2048
	ds_read_b128 v[200:203], v200 offset:3072
	s_cselect_b32 s64, s55, s69
	s_cselect_b32 s65, s53, s70
	s_mov_b32 m0, s24
	s_nop 0
	global_load_lds_dwordx4 v188, s[64:65]
	s_add_u32 s48, s64, 0x2000
	s_addc_u32 s49, s65, 0
	s_mov_b32 m0, s25
	s_nop 0
	global_load_lds_dwordx4 v188, s[48:49]
	s_waitcnt vmcnt(10)
	s_barrier
	s_waitcnt lgkmcnt(3)
	v_mfma_f32_16x16x32_bf16 v[116:119], v[176:179], v[136:139], v[116:119]
	s_waitcnt lgkmcnt(1)
	v_mfma_f32_16x16x32_bf16 v[112:115], v[184:187], v[136:139], v[112:115]
	v_mfma_f32_16x16x32_bf16 v[100:103], v[176:179], v[152:155], v[100:103]
	v_mfma_f32_16x16x32_bf16 v[96:99], v[184:187], v[152:155], v[96:99]
	v_mfma_f32_16x16x32_bf16 v[84:87], v[176:179], v[160:163], v[84:87]
	v_mfma_f32_16x16x32_bf16 v[80:83], v[184:187], v[160:163], v[80:83]
	v_mfma_f32_16x16x32_bf16 v[68:71], v[176:179], v[168:171], v[68:71]
	v_mfma_f32_16x16x32_bf16 v[64:67], v[184:187], v[168:171], v[64:67]
	v_mfma_f32_16x16x32_bf16 v[116:119], v[180:183], v[140:143], v[116:119]
	s_waitcnt lgkmcnt(0)
	v_mfma_f32_16x16x32_bf16 v[112:115], v[200:203], v[140:143], v[112:115]
	v_mfma_f32_16x16x32_bf16 v[100:103], v[180:183], v[156:159], v[100:103]
	v_mfma_f32_16x16x32_bf16 v[96:99], v[200:203], v[156:159], v[96:99]
	v_mfma_f32_16x16x32_bf16 v[84:87], v[180:183], v[164:167], v[84:87]
	v_mfma_f32_16x16x32_bf16 v[80:83], v[200:203], v[164:167], v[80:83]
	v_mfma_f32_16x16x32_bf16 v[68:71], v[180:183], v[172:175], v[68:71]
	v_mfma_f32_16x16x32_bf16 v[64:67], v[200:203], v[172:175], v[64:67]
	s_barrier
	ds_read_b128 v[136:139], v237 offset:16384
	ds_read_b128 v[140:143], v237 offset:17408
	ds_read_b128 v[152:155], v237 offset:18432
	ds_read_b128 v[156:159], v237 offset:19456
	ds_read_b128 v[160:163], v237 offset:20480
	ds_read_b128 v[164:167], v237 offset:21504
	ds_read_b128 v[168:171], v237 offset:22528
	ds_read_b128 v[172:175], v237 offset:23552
	s_mov_b32 m0, s22
	s_nop 0
	global_load_lds_dwordx4 v188, s[60:61]
	s_add_u32 s48, s60, 0x2000
	s_addc_u32 s49, s61, 0
	s_mov_b32 m0, s26
	s_nop 0
	global_load_lds_dwordx4 v188, s[48:49]
	s_barrier
	s_waitcnt lgkmcnt(7)
	v_mfma_f32_16x16x32_bf16 v[60:63], v[120:123], v[136:139], v[60:63]
	v_mfma_f32_16x16x32_bf16 v[56:59], v[128:131], v[136:139], v[56:59]
	s_waitcnt lgkmcnt(5)
	v_mfma_f32_16x16x32_bf16 v[44:47], v[120:123], v[152:155], v[44:47]
	v_mfma_f32_16x16x32_bf16 v[40:43], v[128:131], v[152:155], v[40:43]
	s_waitcnt lgkmcnt(3)
	v_mfma_f32_16x16x32_bf16 v[28:31], v[120:123], v[160:163], v[28:31]
	v_mfma_f32_16x16x32_bf16 v[24:27], v[128:131], v[160:163], v[24:27]
	s_waitcnt lgkmcnt(1)
	v_mfma_f32_16x16x32_bf16 v[12:15], v[120:123], v[168:171], v[12:15]
	v_mfma_f32_16x16x32_bf16 v[8:11], v[128:131], v[168:171], v[8:11]
	v_mfma_f32_16x16x32_bf16 v[60:63], v[124:127], v[140:143], v[60:63]
	v_mfma_f32_16x16x32_bf16 v[56:59], v[132:135], v[140:143], v[56:59]
	v_mfma_f32_16x16x32_bf16 v[44:47], v[124:127], v[156:159], v[44:47]
	v_mfma_f32_16x16x32_bf16 v[40:43], v[132:135], v[156:159], v[40:43]
	v_mfma_f32_16x16x32_bf16 v[28:31], v[124:127], v[164:167], v[28:31]
	v_mfma_f32_16x16x32_bf16 v[24:27], v[132:135], v[164:167], v[24:27]
	s_waitcnt lgkmcnt(0)
	v_mfma_f32_16x16x32_bf16 v[12:15], v[124:127], v[172:175], v[12:15]
	v_mfma_f32_16x16x32_bf16 v[8:11], v[132:135], v[172:175], v[8:11]
	s_barrier
; #define PG8_STAGE(bufoff, gbase, hoff, imm) do { _Pragma("unroll") for (int _i = 0; _i < 2; ++_i) { \
;         asm volatile("s_mov_b32 m0, %0\n\ts_nop 0\n\tglobal_load_lds_dwordx4 %1, %2" \
;             :: "s"(lds0 + (unsigned)((bufoff) + _i * 8192)), "v"(voff0), "s"((const char*)(gbase) + (size_t)(hoff) + (size_t)(_i * 8192)) : "memory"); } } while (0)
; #define PG8_LDA(dst, b, h) do { _Pragma("unroll") for (int m = 0; m < 4; ++m) _Pragma("unroll") for (int k = 0; k < 2; ++k) dst[m][k] = *(const LAS bf16x8*)(lds + PG8_SA(b, h) + aoff + m * 2048 + k * 1024); } while (0)
; #define PG8_LDB(dst, b, h) do { _Pragma("unroll") for (int n = 0; n < 2; ++n) _Pragma("unroll") for (int k = 0; k < 2; ++k) dst[n][k] = *(const LAS bf16x8*)(lds + PG8_SB(b, h) + boff + n * 2048 + k * 1024); } while (0)
; #define PG8_MMA(ai, bj, At, Bt) do { __builtin_amdgcn_s_setprio(1); _Pragma("unroll") for (int m = 0; m < 4; ++m) _Pragma("unroll") for (int n = 0; n < 2; ++n) _Pragma("unroll") for (int k = 0; k < 2; ++k) \
;         acc[ai][bj][m][n] = __builtin_amdgcn_mfma_f32_16x16x32_bf16(Bt[n][k], At[m][k], acc[ai][bj][m][n], 0, 0, 0); __builtin_amdgcn_s_setprio(0); } while (0)
; #define PG8_WAIT_V(n) asm volatile("s_waitcnt vmcnt(" #n ")" ::: "memory")
; #define PG8_WAIT_L(n) asm volatile("s_waitcnt lgkmcnt(" #n ")" ::: "memory")
; #define PG8_BAR __builtin_amdgcn_s_barrier()
; #define PG8_SCHED __builtin_amdgcn_sched_barrier(0)
; template <class Epi>
; __device__ __forceinline__ void gemm_phase(LAS unsigned char* lds, const Gemm g, const StaticOrder& S, const Epi& E) {
;     ...
;             PG8_STAGE(PG8_SB(0, 1), b2, hB, 0);
;             PG8_WAIT_V(6); PG8_BAR; PG8_MMA(1, 1, At, B1); PG8_BAR;
;             PG8_LDB(B0, 1, 0); PG8_SCHED; PG8_LDA(At, 1, 0); PG8_STAGE(PG8_SA(0, 1), a2, hA, 0);
;             PG8_WAIT_L(8); PG8_BAR; PG8_WAIT_L(0); PG8_MMA(0, 0, At, B0); PG8_BAR; PG8_SCHED;
;             PG8_LDB(B1, 1, 1); PG8_STAGE(PG8_SB(1, 0), b2 + KS, 0, 0);
;             PG8_BAR; PG8_WAIT_L(0); PG8_MMA(0, 1, At, B1); PG8_BAR;
;             PG8_LDA(At, 1, 1); PG8_STAGE(PG8_SA(1, 0), a2 + KS, 0, 0);
;             PG8_BAR; PG8_WAIT_L(0); PG8_MMA(1, 0, At, B0); PG8_BAR; PG8_SCHED;
	s_add_u32 s48, s64, 0x80000
	s_addc_u32 s49, s65, 0
	s_mov_b32 m0, s27
	s_nop 0
	global_load_lds_dwordx4 v188, s[48:49]
	s_add_u32 s48, s64, 0x82000
	s_addc_u32 s49, s65, 0
	s_mov_b32 m0, s28
	s_nop 0
	global_load_lds_dwordx4 v188, s[48:49]
	s_waitcnt vmcnt(10)
	s_barrier
	v_mfma_f32_16x16x32_bf16 v[52:55], v[176:179], v[136:139], v[52:55]
	v_mfma_f32_16x16x32_bf16 v[48:51], v[184:187], v[136:139], v[48:51]
	v_mfma_f32_16x16x32_bf16 v[36:39], v[176:179], v[152:155], v[36:39]
	v_mfma_f32_16x16x32_bf16 v[32:35], v[184:187], v[152:155], v[32:35]
	v_mfma_f32_16x16x32_bf16 v[20:23], v[176:179], v[160:163], v[20:23]
	v_mfma_f32_16x16x32_bf16 v[16:19], v[184:187], v[160:163], v[16:19]
	v_mfma_f32_16x16x32_bf16 v[4:7], v[176:179], v[168:171], v[4:7]
	v_mfma_f32_16x16x32_bf16 v[0:3], v[184:187], v[168:171], v[0:3]
	v_mfma_f32_16x16x32_bf16 v[52:55], v[180:183], v[140:143], v[52:55]
	v_mfma_f32_16x16x32_bf16 v[48:51], v[200:203], v[140:143], v[48:51]
	v_mfma_f32_16x16x32_bf16 v[36:39], v[180:183], v[156:159], v[36:39]
	v_mfma_f32_16x16x32_bf16 v[32:35], v[200:203], v[156:159], v[32:35]
	v_mfma_f32_16x16x32_bf16 v[20:23], v[180:183], v[164:167], v[20:23]
	v_mfma_f32_16x16x32_bf16 v[16:19], v[200:203], v[164:167], v[16:19]
	v_mfma_f32_16x16x32_bf16 v[4:7], v[180:183], v[172:175], v[4:7]
	v_mfma_f32_16x16x32_bf16 v[0:3], v[200:203], v[172:175], v[0:3]
	v_add_u32_e32 v132, 0x18000, v236
	s_barrier
	ds_read_b128 v[120:123], v132
	ds_read_b128 v[124:127], v132 offset:1024
	ds_read_b128 v[128:131], v132 offset:2048
	ds_read_b128 v[132:135], v132 offset:3072
	ds_read_b128 v[136:139], v237 offset:32768
	ds_read_b128 v[140:143], v237 offset:33792
	ds_read_b128 v[152:155], v237 offset:34816
	ds_read_b128 v[156:159], v237 offset:35840
	ds_read_b128 v[160:163], v237 offset:36864
	ds_read_b128 v[164:167], v237 offset:37888
	ds_read_b128 v[168:171], v237 offset:38912
	ds_read_b128 v[172:175], v237 offset:39936
	s_add_u32 s48, s60, 0x80000
	s_addc_u32 s49, s61, 0
	s_mov_b32 m0, s29
	s_nop 0
	global_load_lds_dwordx4 v188, s[48:49]
	s_add_u32 s48, s60, 0x82000
	s_addc_u32 s49, s61, 0
	s_mov_b32 m0, s30
	s_nop 0
	global_load_lds_dwordx4 v188, s[48:49]
	s_waitcnt lgkmcnt(8)
	s_waitcnt vmcnt(10)
	s_barrier
	s_waitcnt lgkmcnt(7)
	v_mfma_f32_16x16x32_bf16 v[148:151], v[120:123], v[136:139], v[148:151]
	v_mfma_f32_16x16x32_bf16 v[144:147], v[128:131], v[136:139], v[144:147]
	s_waitcnt lgkmcnt(5)
	v_mfma_f32_16x16x32_bf16 v[108:111], v[120:123], v[152:155], v[108:111]
	v_mfma_f32_16x16x32_bf16 v[104:107], v[128:131], v[152:155], v[104:107]
	s_waitcnt lgkmcnt(3)
	v_mfma_f32_16x16x32_bf16 v[92:95], v[120:123], v[160:163], v[92:95]
	v_mfma_f32_16x16x32_bf16 v[88:91], v[128:131], v[160:163], v[88:91]
	s_waitcnt lgkmcnt(1)
	v_mfma_f32_16x16x32_bf16 v[76:79], v[120:123], v[168:171], v[76:79]
	v_mfma_f32_16x16x32_bf16 v[72:75], v[128:131], v[168:171], v[72:75]
	v_mfma_f32_16x16x32_bf16 v[148:151], v[124:127], v[140:143], v[148:151]
	v_mfma_f32_16x16x32_bf16 v[144:147], v[132:135], v[140:143], v[144:147]
	v_mfma_f32_16x16x32_bf16 v[108:111], v[124:127], v[156:159], v[108:111]
	v_mfma_f32_16x16x32_bf16 v[104:107], v[132:135], v[156:159], v[104:107]
	v_mfma_f32_16x16x32_bf16 v[92:95], v[124:127], v[164:167], v[92:95]
	v_mfma_f32_16x16x32_bf16 v[88:91], v[132:135], v[164:167], v[88:91]
	s_waitcnt lgkmcnt(0)
	v_mfma_f32_16x16x32_bf16 v[76:79], v[124:127], v[172:175], v[76:79]
	v_mfma_f32_16x16x32_bf16 v[72:75], v[132:135], v[172:175], v[72:75]
	s_barrier
	v_add_u32_e32 v200, 0x1c000, v236
	ds_read_b128 v[176:179], v200
	ds_read_b128 v[180:183], v200 offset:1024
	ds_read_b128 v[184:187], v200 offset:2048
	ds_read_b128 v[200:203], v200 offset:3072
	s_add_u32 s48, s64, 0x4000
	s_addc_u32 s49, s65, 0
	s_mov_b32 m0, s39
	s_nop 0
	global_load_lds_dwordx4 v188, s[48:49]
	s_add_u32 s48, s64, 0x6000
	s_addc_u32 s49, s65, 0
	s_mov_b32 m0, s40
	s_nop 0
	global_load_lds_dwordx4 v188, s[48:49]
	s_waitcnt vmcnt(10)
	s_barrier
	s_waitcnt lgkmcnt(3)
	v_mfma_f32_16x16x32_bf16 v[116:119], v[176:179], v[136:139], v[116:119]
	s_waitcnt lgkmcnt(1)
	v_mfma_f32_16x16x32_bf16 v[112:115], v[184:187], v[136:139], v[112:115]
	v_mfma_f32_16x16x32_bf16 v[100:103], v[176:179], v[152:155], v[100:103]
	v_mfma_f32_16x16x32_bf16 v[96:99], v[184:187], v[152:155], v[96:99]
	v_mfma_f32_16x16x32_bf16 v[84:87], v[176:179], v[160:163], v[84:87]
	v_mfma_f32_16x16x32_bf16 v[80:83], v[184:187], v[160:163], v[80:83]
	v_mfma_f32_16x16x32_bf16 v[68:71], v[176:179], v[168:171], v[68:71]
	v_mfma_f32_16x16x32_bf16 v[64:67], v[184:187], v[168:171], v[64:67]
	v_mfma_f32_16x16x32_bf16 v[116:119], v[180:183], v[140:143], v[116:119]
	s_waitcnt lgkmcnt(0)
	v_mfma_f32_16x16x32_bf16 v[112:115], v[200:203], v[140:143], v[112:115]
	v_mfma_f32_16x16x32_bf16 v[100:103], v[180:183], v[156:159], v[100:103]
	v_mfma_f32_16x16x32_bf16 v[96:99], v[200:203], v[156:159], v[96:99]
	v_mfma_f32_16x16x32_bf16 v[84:87], v[180:183], v[164:167], v[84:87]
	v_mfma_f32_16x16x32_bf16 v[80:83], v[200:203], v[164:167], v[80:83]
	v_mfma_f32_16x16x32_bf16 v[68:71], v[180:183], v[172:175], v[68:71]
	v_mfma_f32_16x16x32_bf16 v[64:67], v[200:203], v[172:175], v[64:67]
	s_barrier
	ds_read_b128 v[136:139], v237 offset:49152
	ds_read_b128 v[140:143], v237 offset:50176
	ds_read_b128 v[152:155], v237 offset:51200
	ds_read_b128 v[156:159], v237 offset:52224
	ds_read_b128 v[160:163], v237 offset:53248
	ds_read_b128 v[164:167], v237 offset:54272
	ds_read_b128 v[168:171], v237 offset:55296
	ds_read_b128 v[172:175], v237 offset:56320
	s_add_u32 s48, s60, 0x4000
	s_addc_u32 s49, s61, 0
	s_mov_b32 m0, s41
	s_nop 0
	global_load_lds_dwordx4 v188, s[48:49]
	s_add_u32 s48, s60, 0x6000
	s_addc_u32 s49, s61, 0
	s_mov_b32 m0, s42
	s_nop 0
	global_load_lds_dwordx4 v188, s[48:49]
	s_barrier
; template <class Epi>
; __device__ __forceinline__ void gemm_phase(LAS unsigned char* lds, const Gemm g, const StaticOrder& S, const Epi& E) {
;     ...
;             PG8_BAR; PG8_WAIT_L(0); PG8_MMA(1, 0, At, B0); PG8_BAR; PG8_SCHED;
;             PG8_STAGE(PG8_SB(1, 1), b2 + KS, hB, 0);
;             PG8_WAIT_V(6); PG8_BAR; PG8_MMA(1, 1, At, B1); PG8_BAR;
;     __device__ __forceinline__ void operator()(f32x4 (&acc)[2][2][4][2], const Unit& u, int wr, int wc, int fr, int fq, LAS unsigned char*) const {
;         const int b = u.pm >> 6;
;         const int col0 = u.pn * BM + wc * 32 + 8 * fq;
;         const size_t off0 = (size_t)(u.pm * BM + wr * 64 + fr) * D + col0;
;         f32x4 sc[2][2];
; #pragma unroll
;         for (int bj = 0; bj < 2; ++bj)
; #pragma unroll
;             for (int n = 0; n < 2; ++n) { f32x4 gt = *(const f32x4*)(gate + (size_t)b * MODW + col0 + bj * HALF + n * 4); sc[bj][n] = gt + 1.0f;
;                 if (cs) sc[bj][n] *= *(const f32x4*)(cs + col0 + bj * HALF + n * 4); }
;         if (IN_F32) {
; #pragma unroll
;             for (int ai = 0; ai < 2; ++ai) {
;                 f32x4 r[4][2][2];
; #pragma unroll
;                 for (int m = 0; m < 4; ++m)
; #pragma unroll
;                     for (int bj = 0; bj < 2; ++bj)
; #pragma unroll
;                         for (int n = 0; n < 2; ++n) r[m][bj][n] = *(const f32x4*)((const float*)in + off0 + (size_t)(ai * HALF + m * 16) * D + bj * HALF + n * 4);
; #pragma unroll
;                 for (int m = 0; m < 4; ++m)
; #pragma unroll
;                     for (int bj = 0; bj < 2; ++bj) { const f32x4 r0 = r[m][bj][0] + sc[bj][0] * acc[ai][bj][m][0], r1 = r[m][bj][1] + sc[bj][1] * acc[ai][bj][m][1];
;                         u32x4 w; w.x = cvt_pk_bf16(r0[0], r0[1]); w.y = cvt_pk_bf16(r0[2], r0[3]); w.z = cvt_pk_bf16(r1[0], r1[1]); w.w = cvt_pk_bf16(r1[2], r1[3]);
;                         *(u32x4*)(out + off0 + (size_t)(ai * HALF + m * 16) * D + bj * HALF) = w; }
;                 asm volatile("" ::: "memory");
;             }
;         } else {
;             u32x4 xb[2][4][2];
; #pragma unroll
;             for (int ai = 0; ai < 2; ++ai)
; #pragma unroll
;                 for (int m = 0; m < 4; ++m)
; #pragma unroll
;                     for (int bj = 0; bj < 2; ++bj) xb[ai][m][bj] = *(const u32x4*)((const bf16_t*)in + off0 + (size_t)(ai * HALF + m * 16) * D + bj * HALF);
; #pragma unroll
	s_waitcnt lgkmcnt(7)
	v_mfma_f32_16x16x32_bf16 v[60:63], v[120:123], v[136:139], v[60:63]
	v_mfma_f32_16x16x32_bf16 v[56:59], v[128:131], v[136:139], v[56:59]
	s_waitcnt lgkmcnt(5)
	v_mfma_f32_16x16x32_bf16 v[44:47], v[120:123], v[152:155], v[44:47]
	v_mfma_f32_16x16x32_bf16 v[40:43], v[128:131], v[152:155], v[40:43]
	s_waitcnt lgkmcnt(3)
	v_mfma_f32_16x16x32_bf16 v[28:31], v[120:123], v[160:163], v[28:31]
	v_mfma_f32_16x16x32_bf16 v[24:27], v[128:131], v[160:163], v[24:27]
	s_waitcnt lgkmcnt(1)
	v_mfma_f32_16x16x32_bf16 v[12:15], v[120:123], v[168:171], v[12:15]
	v_mfma_f32_16x16x32_bf16 v[8:11], v[128:131], v[168:171], v[8:11]
	v_mfma_f32_16x16x32_bf16 v[60:63], v[124:127], v[140:143], v[60:63]
	v_mfma_f32_16x16x32_bf16 v[56:59], v[132:135], v[140:143], v[56:59]
	v_mfma_f32_16x16x32_bf16 v[44:47], v[124:127], v[156:159], v[44:47]
	v_mfma_f32_16x16x32_bf16 v[40:43], v[132:135], v[156:159], v[40:43]
	v_mfma_f32_16x16x32_bf16 v[28:31], v[124:127], v[164:167], v[28:31]
	v_mfma_f32_16x16x32_bf16 v[24:27], v[132:135], v[164:167], v[24:27]
	s_waitcnt lgkmcnt(0)
	v_mfma_f32_16x16x32_bf16 v[12:15], v[124:127], v[172:175], v[12:15]
	v_mfma_f32_16x16x32_bf16 v[8:11], v[132:135], v[172:175], v[8:11]
	s_barrier
	s_add_u32 s48, s64, 0x84000
	s_addc_u32 s49, s65, 0
	s_mov_b32 m0, s43
	s_nop 0
	global_load_lds_dwordx4 v188, s[48:49]
	s_add_u32 s48, s64, 0x86000
	s_addc_u32 s49, s65, 0
	s_mov_b32 m0, s66
	s_nop 0
	global_load_lds_dwordx4 v188, s[48:49]
	s_waitcnt vmcnt(10)
	s_barrier
	v_mfma_f32_16x16x32_bf16 v[52:55], v[176:179], v[136:139], v[52:55]
	v_mfma_f32_16x16x32_bf16 v[48:51], v[184:187], v[136:139], v[48:51]
	v_mfma_f32_16x16x32_bf16 v[36:39], v[176:179], v[152:155], v[36:39]
	v_mfma_f32_16x16x32_bf16 v[32:35], v[184:187], v[152:155], v[32:35]
	v_mfma_f32_16x16x32_bf16 v[20:23], v[176:179], v[160:163], v[20:23]
	v_mfma_f32_16x16x32_bf16 v[16:19], v[184:187], v[160:163], v[16:19]
	v_mfma_f32_16x16x32_bf16 v[4:7], v[176:179], v[168:171], v[4:7]
	v_mfma_f32_16x16x32_bf16 v[0:3], v[184:187], v[168:171], v[0:3]
	v_mfma_f32_16x16x32_bf16 v[52:55], v[180:183], v[140:143], v[52:55]
	v_mfma_f32_16x16x32_bf16 v[48:51], v[200:203], v[140:143], v[48:51]
	v_mfma_f32_16x16x32_bf16 v[36:39], v[180:183], v[156:159], v[36:39]
	v_mfma_f32_16x16x32_bf16 v[32:35], v[200:203], v[156:159], v[32:35]
	v_mfma_f32_16x16x32_bf16 v[20:23], v[180:183], v[164:167], v[20:23]
	v_mfma_f32_16x16x32_bf16 v[16:19], v[200:203], v[164:167], v[16:19]
	v_mfma_f32_16x16x32_bf16 v[4:7], v[180:183], v[172:175], v[4:7]
	v_mfma_f32_16x16x32_bf16 v[0:3], v[200:203], v[172:175], v[0:3]
	s_add_i32 s71, s71, 2
	s_add_u32 s69, s69, 0x8000
	s_addc_u32 s70, s70, 0
	s_cmp_gt_u32 s71, 29
	s_mov_b64 s[60:61], s[62:63]
	s_barrier
	s_cbranch_scc0 .LBB0_610
	s_ashr_i32 s0, s50, 6
	s_mul_hi_i32 s1, s0, 0xc000
	s_mul_i32 s0, s0, 0xc000
	v_lshl_or_b32 v128, s51, 8, v234
	s_add_u32 s0, s37, s0
	v_ashrrev_i32_e32 v129, 31, v128
	s_addc_u32 s1, s38, s1
	v_lshl_add_u64 v[130:131], v[128:129], 2, s[0:1]
	global_load_dwordx4 v[208:211], v[130:131], off offset:16
	global_load_dwordx4 v[212:215], v[130:131], off
	global_load_dwordx4 v[200:203], v[130:131], off offset:528
	global_load_dwordx4 v[204:207], v[130:131], off offset:512
	s_mov_b32 s51, s52
	s_mov_b64 s[62:63], s[58:59]
	s_mov_b64 s[60:61], s[56:57]
	v_lshl_add_u32 v120, s50, 8, v233
	v_ashrrev_i32_e32 v121, 31, v120
	v_lshlrev_b64 v[120:121], 11, v[120:121]
	v_lshl_add_u64 v[120:121], v[120:121], 0, v[128:129]
	v_lshlrev_b64 v[216:217], 1, v[120:121]
	v_lshl_add_u64 v[120:121], s[8:9], 0, v[216:217]
	global_load_dwordx4 v[238:241], v[120:121], off
	global_load_dwordx4 v[184:187], v[120:121], off offset:256
	v_add_co_u32_e32 v122, vcc, s45, v120
	s_nop 1
	v_addc_co_u32_e32 v123, vcc, 0, v121, vcc
	global_load_dwordx4 v[180:183], v[122:123], off
	global_load_dwordx4 v[176:179], v[122:123], off offset:256
	v_add_co_u32_e32 v122, vcc, s36, v120
	s_nop 0
	s_nop 0
	v_addc_co_u32_e32 v123, vcc, 0, v121, vcc
	global_load_dwordx4 v[172:175], v[122:123], off
	global_load_dwordx4 v[168:171], v[122:123], off offset:256
	v_add_co_u32_e32 v122, vcc, s23, v120
	s_mov_b32 s50, s54
	s_nop 0
	v_addc_co_u32_e32 v123, vcc, 0, v121, vcc
	global_load_dwordx4 v[164:167], v[122:123], off
	global_load_dwordx4 v[160:163], v[122:123], off offset:256
	v_add_co_u32_e32 v122, vcc, s93, v120
	s_waitcnt vmcnt(7)
	v_pk_add_f32 v[200:201], v[200:201], 1.0 op_sel_hi:[1,0]
	v_pk_add_f32 v[202:203], v[202:203], 1.0 op_sel_hi:[1,0]
	v_pk_add_f32 v[204:205], v[204:205], 1.0 op_sel_hi:[1,0]
	v_pk_add_f32 v[206:207], v[206:207], 1.0 op_sel_hi:[1,0]
	v_pk_add_f32 v[208:209], v[208:209], 1.0 op_sel_hi:[1,0]
	v_pk_add_f32 v[210:211], v[210:211], 1.0 op_sel_hi:[1,0]
	v_pk_add_f32 v[212:213], v[212:213], 1.0 op_sel_hi:[1,0]
	v_pk_add_f32 v[214:215], v[214:215], 1.0 op_sel_hi:[1,0]
	v_lshlrev_b32_e32 v230, 16, v238
	v_addc_co_u32_e32 v123, vcc, 0, v121, vcc
	global_load_dwordx4 v[156:159], v[122:123], off
	global_load_dwordx4 v[152:155], v[122:123], off offset:256
	v_add_co_u32_e32 v122, vcc, s33, v120
	v_and_b32_e32 v231, 0xffff0000, v238
	s_nop 0
	v_addc_co_u32_e32 v123, vcc, 0, v121, vcc
	global_load_dwordx4 v[140:143], v[122:123], off
	global_load_dwordx4 v[136:139], v[122:123], off offset:256
	v_add_co_u32_e32 v122, vcc, s18, v120
	v_lshlrev_b32_e32 v242, 16, v240
	s_nop 0
	v_addc_co_u32_e32 v123, vcc, 0, v121, vcc
	global_load_dwordx4 v[132:135], v[122:123], off
	global_load_dwordx4 v[128:131], v[122:123], off offset:256
	v_add_co_u32_e32 v120, vcc, s19, v120
	v_and_b32_e32 v243, 0xffff0000, v240
	s_nop 0
	v_addc_co_u32_e32 v121, vcc, 0, v121, vcc
	global_load_dwordx4 v[124:127], v[120:121], off
	s_nop 0
	global_load_dwordx4 v[120:123], v[120:121], off offset:256
	v_lshlrev_b32_e32 v238, 16, v239
	v_and_b32_e32 v239, 0xffff0000, v239
	v_lshlrev_b32_e32 v240, 16, v241
	v_and_b32_e32 v241, 0xffff0000, v241
	v_pk_fma_f32 v[148:149], v[148:149], v[212:213], v[230:231]
	v_pk_fma_f32 v[144:145], v[144:145], v[208:209], v[242:243]
	v_pk_fma_f32 v[150:151], v[150:151], v[214:215], v[238:239]
	v_pk_fma_f32 v[230:231], v[146:147], v[210:211], v[240:241]
	v_cvt_pk_bf16_f32 v146, v148, v149
	v_cvt_pk_bf16_f32 v147, v150, v151
	v_cvt_pk_bf16_f32 v148, v144, v145
	v_lshl_add_u64 v[144:145], s[10:11], 0, v[216:217]
	v_cvt_pk_bf16_f32 v149, v230, v231
	global_store_dwordx4 v[144:145], v[146:149], off
	s_waitcnt vmcnt(15)
; __device__ __forceinline__ unsigned cvt_pk_bf16(float lo, float hi) { unsigned r; asm volatile("v_cvt_pk_bf16_f32 %0, %1, %2" : "=v"(r) : "v"(lo), "v"(hi)); return r; }
;     __device__ __forceinline__ void operator()(f32x4 (&acc)[2][2][4][2], const Unit& u, int wr, int wc, int fr, int fq, LAS unsigned char*) const {
;     ...
; #pragma unroll
;             for (int ai = 0; ai < 2; ++ai)
; #pragma unroll
;                 for (int m = 0; m < 4; ++m)
; #pragma unroll
;                     for (int bj = 0; bj < 2; ++bj) { const u32x4 x = xb[ai][m][bj];
;                         f32x4 r0 = (f32x4){__uint_as_float(x.x << 16), __uint_as_float(x.x & 0xffff0000u), __uint_as_float(x.y << 16), __uint_as_float(x.y & 0xffff0000u)};
;                         f32x4 r1 = (f32x4){__uint_as_float(x.z << 16), __uint_as_float(x.z & 0xffff0000u), __uint_as_float(x.w << 16), __uint_as_float(x.w & 0xffff0000u)};
;                         r0 += sc[bj][0] * acc[ai][bj][m][0]; r1 += sc[bj][1] * acc[ai][bj][m][1];
;                         u32x4 w; w.x = cvt_pk_bf16(r0[0], r0[1]); w.y = cvt_pk_bf16(r0[2], r0[3]); w.z = cvt_pk_bf16(r1[0], r1[1]); w.w = cvt_pk_bf16(r1[2], r1[3]);
;                         *(u32x4*)(out + off0 + (size_t)(ai * HALF + m * 16) * D + bj * HALF) = w; }
	v_lshlrev_b32_e32 v150, 16, v186
	v_and_b32_e32 v151, 0xffff0000, v186
	v_lshlrev_b32_e32 v146, 16, v184
	v_and_b32_e32 v147, 0xffff0000, v184
	v_lshlrev_b32_e32 v148, 16, v185
	v_and_b32_e32 v149, 0xffff0000, v185
	v_lshlrev_b32_e32 v184, 16, v187
	v_and_b32_e32 v185, 0xffff0000, v187
	v_pk_fma_f32 v[118:119], v[118:119], v[206:207], v[148:149]
	v_pk_fma_f32 v[116:117], v[116:117], v[204:205], v[146:147]
	v_pk_fma_f32 v[146:147], v[114:115], v[202:203], v[184:185]
	v_pk_fma_f32 v[114:115], v[112:113], v[200:201], v[150:151]
	v_cvt_pk_bf16_f32 v112, v116, v117
	v_cvt_pk_bf16_f32 v113, v118, v119
	s_waitcnt vmcnt(14)
	v_lshlrev_b32_e32 v116, 16, v182
	v_cvt_pk_bf16_f32 v114, v114, v115
	v_cvt_pk_bf16_f32 v115, v146, v147
	global_store_dwordx4 v[144:145], v[112:115], off offset:256
	v_and_b32_e32 v117, 0xffff0000, v182
	v_lshlrev_b32_e32 v118, 16, v183
	v_lshlrev_b32_e32 v112, 16, v180
	v_and_b32_e32 v113, 0xffff0000, v180
	v_and_b32_e32 v119, 0xffff0000, v183
	v_pk_fma_f32 v[108:109], v[108:109], v[212:213], v[112:113]
	v_lshlrev_b32_e32 v114, 16, v181
	v_and_b32_e32 v115, 0xffff0000, v181
	v_pk_fma_f32 v[112:113], v[106:107], v[210:211], v[118:119]
	v_pk_fma_f32 v[106:107], v[104:105], v[208:209], v[116:117]
	v_cvt_pk_bf16_f32 v104, v108, v109
	v_add_co_u32_e32 v108, vcc, s45, v144
	v_pk_fma_f32 v[110:111], v[110:111], v[214:215], v[114:115]
	s_nop 0
	v_addc_co_u32_e32 v109, vcc, 0, v145, vcc
	v_cvt_pk_bf16_f32 v105, v110, v111
	v_cvt_pk_bf16_f32 v106, v106, v107
	v_cvt_pk_bf16_f32 v107, v112, v113
	global_store_dwordx4 v[108:109], v[104:107], off
	s_waitcnt vmcnt(15)
	v_lshlrev_b32_e32 v110, 16, v178
	v_and_b32_e32 v111, 0xffff0000, v178
	v_lshlrev_b32_e32 v104, 16, v176
	v_and_b32_e32 v105, 0xffff0000, v176
	v_lshlrev_b32_e32 v106, 16, v177
	v_and_b32_e32 v107, 0xffff0000, v177
	v_lshlrev_b32_e32 v112, 16, v179
	v_and_b32_e32 v113, 0xffff0000, v179
	v_pk_fma_f32 v[102:103], v[102:103], v[206:207], v[106:107]
	v_pk_fma_f32 v[100:101], v[100:101], v[204:205], v[104:105]
	v_pk_fma_f32 v[104:105], v[98:99], v[202:203], v[112:113]
	v_pk_fma_f32 v[98:99], v[96:97], v[200:201], v[110:111]
	v_cvt_pk_bf16_f32 v96, v100, v101
	v_cvt_pk_bf16_f32 v97, v102, v103
	s_waitcnt vmcnt(14)
	v_lshlrev_b32_e32 v100, 16, v174
	v_cvt_pk_bf16_f32 v98, v98, v99
	v_cvt_pk_bf16_f32 v99, v104, v105
	global_store_dwordx4 v[108:109], v[96:99], off offset:256
	v_and_b32_e32 v101, 0xffff0000, v174
	v_lshlrev_b32_e32 v102, 16, v175
	v_lshlrev_b32_e32 v96, 16, v172
	v_and_b32_e32 v97, 0xffff0000, v172
	v_and_b32_e32 v103, 0xffff0000, v175
	v_pk_fma_f32 v[92:93], v[92:93], v[212:213], v[96:97]
	v_lshlrev_b32_e32 v98, 16, v173
	v_and_b32_e32 v99, 0xffff0000, v173
	v_pk_fma_f32 v[96:97], v[90:91], v[210:211], v[102:103]
	v_pk_fma_f32 v[90:91], v[88:89], v[208:209], v[100:101]
	v_cvt_pk_bf16_f32 v88, v92, v93
	v_add_co_u32_e32 v92, vcc, s36, v144
	v_pk_fma_f32 v[94:95], v[94:95], v[214:215], v[98:99]
	s_nop 0
	v_addc_co_u32_e32 v93, vcc, 0, v145, vcc
	v_cvt_pk_bf16_f32 v89, v94, v95
	v_cvt_pk_bf16_f32 v90, v90, v91
	v_cvt_pk_bf16_f32 v91, v96, v97
	global_store_dwordx4 v[92:93], v[88:91], off
	s_waitcnt vmcnt(15)
	v_lshlrev_b32_e32 v94, 16, v170
	v_and_b32_e32 v95, 0xffff0000, v170
	v_lshlrev_b32_e32 v88, 16, v168
	v_and_b32_e32 v89, 0xffff0000, v168
	v_lshlrev_b32_e32 v90, 16, v169
	v_and_b32_e32 v91, 0xffff0000, v169
	v_lshlrev_b32_e32 v96, 16, v171
	v_and_b32_e32 v97, 0xffff0000, v171
	v_pk_fma_f32 v[86:87], v[86:87], v[206:207], v[90:91]
	v_pk_fma_f32 v[84:85], v[84:85], v[204:205], v[88:89]
	v_pk_fma_f32 v[88:89], v[82:83], v[202:203], v[96:97]
	v_pk_fma_f32 v[82:83], v[80:81], v[200:201], v[94:95]
	v_cvt_pk_bf16_f32 v80, v84, v85
	v_cvt_pk_bf16_f32 v81, v86, v87
	s_waitcnt vmcnt(14)
	v_lshlrev_b32_e32 v84, 16, v166
	v_cvt_pk_bf16_f32 v82, v82, v83
	v_cvt_pk_bf16_f32 v83, v88, v89
	global_store_dwordx4 v[92:93], v[80:83], off offset:256
	v_and_b32_e32 v85, 0xffff0000, v166
	v_lshlrev_b32_e32 v86, 16, v167
	v_lshlrev_b32_e32 v80, 16, v164
	v_and_b32_e32 v81, 0xffff0000, v164
	v_and_b32_e32 v87, 0xffff0000, v167
	v_pk_fma_f32 v[76:77], v[76:77], v[212:213], v[80:81]
	v_lshlrev_b32_e32 v82, 16, v165
	v_and_b32_e32 v83, 0xffff0000, v165
	v_pk_fma_f32 v[80:81], v[74:75], v[210:211], v[86:87]
	v_pk_fma_f32 v[74:75], v[72:73], v[208:209], v[84:85]
	v_cvt_pk_bf16_f32 v72, v76, v77
	v_add_co_u32_e32 v76, vcc, s23, v144
	v_pk_fma_f32 v[78:79], v[78:79], v[214:215], v[82:83]
	s_nop 0
	v_addc_co_u32_e32 v77, vcc, 0, v145, vcc
	v_cvt_pk_bf16_f32 v73, v78, v79
	v_cvt_pk_bf16_f32 v74, v74, v75
	v_cvt_pk_bf16_f32 v75, v80, v81
	global_store_dwordx4 v[76:77], v[72:75], off
	s_waitcnt vmcnt(15)
	v_lshlrev_b32_e32 v78, 16, v162
	v_and_b32_e32 v79, 0xffff0000, v162
	v_lshlrev_b32_e32 v72, 16, v160
	v_and_b32_e32 v73, 0xffff0000, v160
	v_lshlrev_b32_e32 v74, 16, v161
	v_and_b32_e32 v75, 0xffff0000, v161
	v_lshlrev_b32_e32 v80, 16, v163
	v_and_b32_e32 v81, 0xffff0000, v163
	v_pk_fma_f32 v[70:71], v[70:71], v[206:207], v[74:75]
	v_pk_fma_f32 v[68:69], v[68:69], v[204:205], v[72:73]
	v_pk_fma_f32 v[72:73], v[66:67], v[202:203], v[80:81]
	v_pk_fma_f32 v[66:67], v[64:65], v[200:201], v[78:79]
	v_cvt_pk_bf16_f32 v64, v68, v69
	v_cvt_pk_bf16_f32 v65, v70, v71
	s_waitcnt vmcnt(14)
; __device__ __forceinline__ unsigned cvt_pk_bf16(float lo, float hi) { unsigned r; asm volatile("v_cvt_pk_bf16_f32 %0, %1, %2" : "=v"(r) : "v"(lo), "v"(hi)); return r; }
; #define PG8_WAIT_V(n) asm volatile("s_waitcnt vmcnt(" #n ")" ::: "memory")
; #define PG8_BAR __builtin_amdgcn_s_barrier()
; template <class Epi>
; __device__ __forceinline__ void gemm_phase(LAS unsigned char* lds, const Gemm g, const StaticOrder& S, const Epi& E) {
;     ...
;         if (!has_next) break;
; #pragma unroll
;         for (int a = 0; a < 2; ++a)
; #pragma unroll
;             for (int b = 0; b < 2; ++b)
; #pragma unroll
;                 for (int m = 0; m < 4; ++m)
; #pragma unroll
;                     for (int n = 0; n < 2; ++n) acc[a][b][m][n] = (f32x4){0.f, 0.f, 0.f, 0.f};
;         cur = nxt; cA = nA; cB = nB; ++ui;
;     }
;     PG8_WAIT_V(0);
;     if (wr == 0) PG8_BAR;
;     PG8_BAR;
;     __device__ __forceinline__ void operator()(f32x4 (&acc)[2][2][4][2], const Unit& u, int wr, int wc, int fr, int fq, LAS unsigned char*) const {
;     ...
; #pragma unroll
;             for (int ai = 0; ai < 2; ++ai)
; #pragma unroll
;                 for (int m = 0; m < 4; ++m)
; #pragma unroll
;                     for (int bj = 0; bj < 2; ++bj) { const u32x4 x = xb[ai][m][bj];
;                         f32x4 r0 = (f32x4){__uint_as_float(x.x << 16), __uint_as_float(x.x & 0xffff0000u), __uint_as_float(x.y << 16), __uint_as_float(x.y & 0xffff0000u)};
;                         f32x4 r1 = (f32x4){__uint_as_float(x.z << 16), __uint_as_float(x.z & 0xffff0000u), __uint_as_float(x.w << 16), __uint_as_float(x.w & 0xffff0000u)};
;                         r0 += sc[bj][0] * acc[ai][bj][m][0]; r1 += sc[bj][1] * acc[ai][bj][m][1];
;                         u32x4 w; w.x = cvt_pk_bf16(r0[0], r0[1]); w.y = cvt_pk_bf16(r0[2], r0[3]); w.z = cvt_pk_bf16(r1[0], r1[1]); w.w = cvt_pk_bf16(r1[2], r1[3]);
;                         *(u32x4*)(out + off0 + (size_t)(ai * HALF + m * 16) * D + bj * HALF) = w; }
	v_lshlrev_b32_e32 v68, 16, v158
	v_cvt_pk_bf16_f32 v66, v66, v67
	v_cvt_pk_bf16_f32 v67, v72, v73
	global_store_dwordx4 v[76:77], v[64:67], off offset:256
	v_and_b32_e32 v69, 0xffff0000, v158
	v_lshlrev_b32_e32 v70, 16, v159
	v_lshlrev_b32_e32 v64, 16, v156
	v_and_b32_e32 v65, 0xffff0000, v156
	v_and_b32_e32 v71, 0xffff0000, v159
	v_pk_fma_f32 v[60:61], v[60:61], v[212:213], v[64:65]
	v_lshlrev_b32_e32 v66, 16, v157
	v_and_b32_e32 v67, 0xffff0000, v157
	v_pk_fma_f32 v[64:65], v[58:59], v[210:211], v[70:71]
	v_pk_fma_f32 v[58:59], v[56:57], v[208:209], v[68:69]
	v_cvt_pk_bf16_f32 v56, v60, v61
	v_add_co_u32_e32 v60, vcc, s93, v144
	v_pk_fma_f32 v[62:63], v[62:63], v[214:215], v[66:67]
	s_nop 0
	v_addc_co_u32_e32 v61, vcc, 0, v145, vcc
	v_cvt_pk_bf16_f32 v57, v62, v63
	v_cvt_pk_bf16_f32 v58, v58, v59
	v_cvt_pk_bf16_f32 v59, v64, v65
	global_store_dwordx4 v[60:61], v[56:59], off
	s_waitcnt vmcnt(15)
	v_lshlrev_b32_e32 v62, 16, v154
	v_and_b32_e32 v63, 0xffff0000, v154
	v_lshlrev_b32_e32 v56, 16, v152
	v_and_b32_e32 v57, 0xffff0000, v152
	v_lshlrev_b32_e32 v58, 16, v153
	v_and_b32_e32 v59, 0xffff0000, v153
	v_lshlrev_b32_e32 v64, 16, v155
	v_and_b32_e32 v65, 0xffff0000, v155
	v_pk_fma_f32 v[54:55], v[54:55], v[206:207], v[58:59]
	v_pk_fma_f32 v[52:53], v[52:53], v[204:205], v[56:57]
	v_pk_fma_f32 v[56:57], v[50:51], v[202:203], v[64:65]
	v_pk_fma_f32 v[50:51], v[48:49], v[200:201], v[62:63]
	v_cvt_pk_bf16_f32 v48, v52, v53
	v_cvt_pk_bf16_f32 v49, v54, v55
	s_waitcnt vmcnt(14)
	v_lshlrev_b32_e32 v52, 16, v142
	v_cvt_pk_bf16_f32 v50, v50, v51
	v_cvt_pk_bf16_f32 v51, v56, v57
	global_store_dwordx4 v[60:61], v[48:51], off offset:256
	v_and_b32_e32 v53, 0xffff0000, v142
	v_lshlrev_b32_e32 v54, 16, v143
	v_lshlrev_b32_e32 v48, 16, v140
	v_and_b32_e32 v49, 0xffff0000, v140
	v_and_b32_e32 v55, 0xffff0000, v143
	v_pk_fma_f32 v[44:45], v[44:45], v[212:213], v[48:49]
	v_lshlrev_b32_e32 v50, 16, v141
	v_and_b32_e32 v51, 0xffff0000, v141
	v_pk_fma_f32 v[48:49], v[42:43], v[210:211], v[54:55]
	v_pk_fma_f32 v[42:43], v[40:41], v[208:209], v[52:53]
	v_cvt_pk_bf16_f32 v40, v44, v45
	v_add_co_u32_e32 v44, vcc, s33, v144
	v_pk_fma_f32 v[46:47], v[46:47], v[214:215], v[50:51]
	s_nop 0
	v_addc_co_u32_e32 v45, vcc, 0, v145, vcc
	v_cvt_pk_bf16_f32 v41, v46, v47
	v_cvt_pk_bf16_f32 v42, v42, v43
	v_cvt_pk_bf16_f32 v43, v48, v49
	global_store_dwordx4 v[44:45], v[40:43], off
	s_waitcnt vmcnt(15)
	v_lshlrev_b32_e32 v46, 16, v138
	v_and_b32_e32 v47, 0xffff0000, v138
	v_lshlrev_b32_e32 v40, 16, v136
	v_and_b32_e32 v41, 0xffff0000, v136
	v_lshlrev_b32_e32 v42, 16, v137
	v_and_b32_e32 v43, 0xffff0000, v137
	v_lshlrev_b32_e32 v48, 16, v139
	v_and_b32_e32 v49, 0xffff0000, v139
	v_pk_fma_f32 v[38:39], v[38:39], v[206:207], v[42:43]
	v_pk_fma_f32 v[36:37], v[36:37], v[204:205], v[40:41]
	v_pk_fma_f32 v[40:41], v[34:35], v[202:203], v[48:49]
	v_pk_fma_f32 v[34:35], v[32:33], v[200:201], v[46:47]
	v_cvt_pk_bf16_f32 v32, v36, v37
	v_cvt_pk_bf16_f32 v33, v38, v39
	s_waitcnt vmcnt(14)
	v_lshlrev_b32_e32 v36, 16, v134
	v_cvt_pk_bf16_f32 v34, v34, v35
	v_cvt_pk_bf16_f32 v35, v40, v41
	global_store_dwordx4 v[44:45], v[32:35], off offset:256
	v_and_b32_e32 v37, 0xffff0000, v134
	v_lshlrev_b32_e32 v38, 16, v135
	v_lshlrev_b32_e32 v32, 16, v132
	v_and_b32_e32 v33, 0xffff0000, v132
	v_and_b32_e32 v39, 0xffff0000, v135
	v_pk_fma_f32 v[28:29], v[28:29], v[212:213], v[32:33]
	v_lshlrev_b32_e32 v34, 16, v133
	v_and_b32_e32 v35, 0xffff0000, v133
	v_pk_fma_f32 v[32:33], v[26:27], v[210:211], v[38:39]
	v_pk_fma_f32 v[26:27], v[24:25], v[208:209], v[36:37]
	v_cvt_pk_bf16_f32 v24, v28, v29
	v_add_co_u32_e32 v28, vcc, s18, v144
	v_pk_fma_f32 v[30:31], v[30:31], v[214:215], v[34:35]
	s_nop 0
	v_addc_co_u32_e32 v29, vcc, 0, v145, vcc
	v_cvt_pk_bf16_f32 v25, v30, v31
	v_cvt_pk_bf16_f32 v26, v26, v27
	v_cvt_pk_bf16_f32 v27, v32, v33
	global_store_dwordx4 v[28:29], v[24:27], off
	s_waitcnt vmcnt(15)
	v_lshlrev_b32_e32 v30, 16, v130
	v_and_b32_e32 v31, 0xffff0000, v130
	v_lshlrev_b32_e32 v24, 16, v128
	v_and_b32_e32 v25, 0xffff0000, v128
	v_lshlrev_b32_e32 v26, 16, v129
	v_and_b32_e32 v27, 0xffff0000, v129
	v_lshlrev_b32_e32 v32, 16, v131
	v_and_b32_e32 v33, 0xffff0000, v131
	v_pk_fma_f32 v[22:23], v[22:23], v[206:207], v[26:27]
	v_pk_fma_f32 v[20:21], v[20:21], v[204:205], v[24:25]
	v_pk_fma_f32 v[24:25], v[18:19], v[202:203], v[32:33]
	v_pk_fma_f32 v[18:19], v[16:17], v[200:201], v[30:31]
	v_cvt_pk_bf16_f32 v16, v20, v21
	v_cvt_pk_bf16_f32 v17, v22, v23
	s_waitcnt vmcnt(14)
	v_lshlrev_b32_e32 v20, 16, v126
	v_cvt_pk_bf16_f32 v18, v18, v19
	v_cvt_pk_bf16_f32 v19, v24, v25
	global_store_dwordx4 v[28:29], v[16:19], off offset:256
	v_and_b32_e32 v21, 0xffff0000, v126
	v_lshlrev_b32_e32 v22, 16, v127
	v_lshlrev_b32_e32 v16, 16, v124
	v_and_b32_e32 v17, 0xffff0000, v124
	v_and_b32_e32 v23, 0xffff0000, v127
	v_pk_fma_f32 v[12:13], v[12:13], v[212:213], v[16:17]
	v_lshlrev_b32_e32 v18, 16, v125
	v_and_b32_e32 v19, 0xffff0000, v125
	v_pk_fma_f32 v[16:17], v[10:11], v[210:211], v[22:23]
	v_pk_fma_f32 v[10:11], v[8:9], v[208:209], v[20:21]
	v_cvt_pk_bf16_f32 v8, v12, v13
	v_add_co_u32_e32 v12, vcc, s19, v144
	v_pk_fma_f32 v[14:15], v[14:15], v[214:215], v[18:19]
	s_nop 0
	v_addc_co_u32_e32 v13, vcc, 0, v145, vcc
	v_cvt_pk_bf16_f32 v9, v14, v15
	v_cvt_pk_bf16_f32 v10, v10, v11
	v_cvt_pk_bf16_f32 v11, v16, v17
	global_store_dwordx4 v[12:13], v[8:11], off
	s_waitcnt vmcnt(15)
	v_lshlrev_b32_e32 v14, 16, v122
	v_and_b32_e32 v15, 0xffff0000, v122
	v_lshlrev_b32_e32 v8, 16, v120
	v_and_b32_e32 v9, 0xffff0000, v120
	v_lshlrev_b32_e32 v16, 16, v123
	v_and_b32_e32 v17, 0xffff0000, v123
	v_lshlrev_b32_e32 v10, 16, v121
	v_and_b32_e32 v11, 0xffff0000, v121
	v_pk_fma_f32 v[4:5], v[4:5], v[204:205], v[8:9]
	v_pk_fma_f32 v[8:9], v[2:3], v[202:203], v[16:17]
	v_pk_fma_f32 v[2:3], v[0:1], v[200:201], v[14:15]
	s_and_b64 vcc, exec, s[4:5]
	v_pk_fma_f32 v[6:7], v[6:7], v[206:207], v[10:11]
	v_cvt_pk_bf16_f32 v0, v4, v5
	s_nop 0
	v_cvt_pk_bf16_f32 v1, v6, v7
	v_cvt_pk_bf16_f32 v2, v2, v3
	v_cvt_pk_bf16_f32 v3, v8, v9
	global_store_dwordx4 v[12:13], v[0:3], off offset:256
	s_cbranch_vccz .LBB0_603
	s_waitcnt vmcnt(0)
	s_cmpk_gt_u32 s16, 0xff
	v_readlane_b32 s38, v255, 44
	s_movk_i32 s30, 0x7ff
	s_cbranch_scc1 .LBB0_614
	s_barrier

; #define PG8_STAGE(bufoff, gbase, hoff, imm) do { _Pragma("unroll") for (int _i = 0; _i < 2; ++_i) { \
;         asm volatile("s_mov_b32 m0, %0\n\ts_nop 0\n\tglobal_load_lds_dwordx4 %1, %2" \
;             :: "s"(lds0 + (unsigned)((bufoff) + _i * 8192)), "v"(voff0), "s"((const char*)(gbase) + (size_t)(hoff) + (size_t)(_i * 8192)) : "memory"); } } while (0)
; #define PG8_LDA(dst, b, h) do { _Pragma("unroll") for (int m = 0; m < 4; ++m) _Pragma("unroll") for (int k = 0; k < 2; ++k) dst[m][k] = *(const LAS bf16x8*)(lds + PG8_SA(b, h) + aoff + m * 2048 + k * 1024); } while (0)
; #define PG8_LDB(dst, b, h) do { _Pragma("unroll") for (int n = 0; n < 2; ++n) _Pragma("unroll") for (int k = 0; k < 2; ++k) dst[n][k] = *(const LAS bf16x8*)(lds + PG8_SB(b, h) + boff + n * 2048 + k * 1024); } while (0)
; #define PG8_MMA(ai, bj, At, Bt) do { __builtin_amdgcn_s_setprio(1); _Pragma("unroll") for (int m = 0; m < 4; ++m) _Pragma("unroll") for (int n = 0; n < 2; ++n) _Pragma("unroll") for (int k = 0; k < 2; ++k) \
;         acc[ai][bj][m][n] = __builtin_amdgcn_mfma_f32_16x16x32_bf16(Bt[n][k], At[m][k], acc[ai][bj][m][n], 0, 0, 0); __builtin_amdgcn_s_setprio(0); } while (0)
; #define PG8_WAIT_V(n) asm volatile("s_waitcnt vmcnt(" #n ")" ::: "memory")
; #define PG8_WAIT_L(n) asm volatile("s_waitcnt lgkmcnt(" #n ")" ::: "memory")
; #define PG8_BAR __builtin_amdgcn_s_barrier()
; #define PG8_SCHED __builtin_amdgcn_sched_barrier(0)
; template <class Epi>
; __device__ __forceinline__ void gemm_phase(LAS unsigned char* lds, const Gemm g, const StaticOrder& S, const Epi& E) {
;     ...
;             PG8_LDB(B0, 0, 0); PG8_SCHED; PG8_LDA(At, 0, 0); PG8_STAGE(PG8_SA(1, 1), aT + KS, hA, 0);
;             PG8_WAIT_L(8); PG8_BAR; PG8_WAIT_L(0); PG8_MMA(0, 0, At, B0); PG8_BAR; PG8_SCHED;
;             PG8_LDB(B1, 0, 1); PG8_STAGE(PG8_SB(0, 0), b2, 0, 0);
;             PG8_BAR; PG8_WAIT_L(0); PG8_MMA(0, 1, At, B1); PG8_BAR;
;             PG8_LDA(At, 0, 1); PG8_STAGE(PG8_SA(0, 0), a2, 0, 0);
;             PG8_BAR; PG8_WAIT_L(0); PG8_MMA(1, 0, At, B0); PG8_BAR; PG8_SCHED;
;             PG8_STAGE(PG8_SB(0, 1), b2, hB, 0);
;             PG8_WAIT_V(6); PG8_BAR; PG8_MMA(1, 1, At, B1); PG8_BAR;
.LBB0_860:
	s_add_u32 s58, s56, 0x8000
	v_add_u32_e32 v132, 0x10000, v236
	s_addc_u32 s59, s57, 0
	ds_read_b128 v[120:123], v132
	ds_read_b128 v[124:127], v132 offset:1024
	ds_read_b128 v[128:131], v132 offset:2048
	ds_read_b128 v[132:135], v132 offset:3072
	s_add_u32 s48, s56, 0x164000
	s_addc_u32 s49, s57, 0
	s_add_u32 s60, s56, 0x166000
	s_addc_u32 s61, s57, 0
	s_cmpk_eq_i32 s69, 0x54
	s_cselect_b32 s57, s7, s59
	s_cselect_b32 s56, s6, s58
	ds_read_b128 v[136:139], v237
	ds_read_b128 v[140:143], v237 offset:1024
	ds_read_b128 v[152:155], v237 offset:2048
	ds_read_b128 v[156:159], v237 offset:3072
	ds_read_b128 v[160:163], v237 offset:4096
	ds_read_b128 v[164:167], v237 offset:5120
	ds_read_b128 v[168:171], v237 offset:6144
	ds_read_b128 v[172:175], v237 offset:7168
	s_mov_b32 m0, s65
	s_nop 0
	global_load_lds_dwordx4 v188, s[48:49]
	s_mov_b32 m0, s66
	s_nop 0
	global_load_lds_dwordx4 v188, s[60:61]
	s_waitcnt lgkmcnt(8)
	s_waitcnt vmcnt(10)
	s_barrier
	s_waitcnt lgkmcnt(7)
	v_mfma_f32_16x16x32_bf16 v[148:151], v[120:123], v[136:139], v[148:151]
	v_mfma_f32_16x16x32_bf16 v[144:147], v[128:131], v[136:139], v[144:147]
	s_waitcnt lgkmcnt(5)
	v_mfma_f32_16x16x32_bf16 v[108:111], v[120:123], v[152:155], v[108:111]
	v_mfma_f32_16x16x32_bf16 v[104:107], v[128:131], v[152:155], v[104:107]
	s_waitcnt lgkmcnt(3)
	v_mfma_f32_16x16x32_bf16 v[92:95], v[120:123], v[160:163], v[92:95]
	v_mfma_f32_16x16x32_bf16 v[88:91], v[128:131], v[160:163], v[88:91]
	s_waitcnt lgkmcnt(1)
	v_mfma_f32_16x16x32_bf16 v[76:79], v[120:123], v[168:171], v[76:79]
	v_mfma_f32_16x16x32_bf16 v[72:75], v[128:131], v[168:171], v[72:75]
	v_mfma_f32_16x16x32_bf16 v[148:151], v[124:127], v[140:143], v[148:151]
	v_mfma_f32_16x16x32_bf16 v[144:147], v[132:135], v[140:143], v[144:147]
	v_mfma_f32_16x16x32_bf16 v[108:111], v[124:127], v[156:159], v[108:111]
	v_mfma_f32_16x16x32_bf16 v[104:107], v[132:135], v[156:159], v[104:107]
	v_mfma_f32_16x16x32_bf16 v[92:95], v[124:127], v[164:167], v[92:95]
	v_mfma_f32_16x16x32_bf16 v[88:91], v[132:135], v[164:167], v[88:91]
	s_waitcnt lgkmcnt(0)
	v_mfma_f32_16x16x32_bf16 v[76:79], v[124:127], v[172:175], v[76:79]
	v_mfma_f32_16x16x32_bf16 v[72:75], v[132:135], v[172:175], v[72:75]
	s_barrier
	v_add_u32_e32 v200, 0x14000, v236
	ds_read_b128 v[176:179], v200
	ds_read_b128 v[180:183], v200 offset:1024
	ds_read_b128 v[184:187], v200 offset:2048
	ds_read_b128 v[200:203], v200 offset:3072
	s_cselect_b32 s60, s8, s0
	s_cselect_b32 s61, s9, s1
	s_mov_b32 m0, s26
	s_nop 0
	global_load_lds_dwordx4 v188, s[60:61]
	s_add_u32 s48, s60, 0x2000
	s_addc_u32 s49, s61, 0
	s_mov_b32 m0, s27
	s_nop 0
	global_load_lds_dwordx4 v188, s[48:49]
	s_waitcnt vmcnt(10)
	s_barrier
	s_waitcnt lgkmcnt(3)
	v_mfma_f32_16x16x32_bf16 v[116:119], v[176:179], v[136:139], v[116:119]
	s_waitcnt lgkmcnt(1)
	v_mfma_f32_16x16x32_bf16 v[112:115], v[184:187], v[136:139], v[112:115]
	v_mfma_f32_16x16x32_bf16 v[100:103], v[176:179], v[152:155], v[100:103]
	v_mfma_f32_16x16x32_bf16 v[96:99], v[184:187], v[152:155], v[96:99]
	v_mfma_f32_16x16x32_bf16 v[84:87], v[176:179], v[160:163], v[84:87]
	v_mfma_f32_16x16x32_bf16 v[80:83], v[184:187], v[160:163], v[80:83]
	v_mfma_f32_16x16x32_bf16 v[68:71], v[176:179], v[168:171], v[68:71]
	v_mfma_f32_16x16x32_bf16 v[64:67], v[184:187], v[168:171], v[64:67]
	v_mfma_f32_16x16x32_bf16 v[116:119], v[180:183], v[140:143], v[116:119]
	s_waitcnt lgkmcnt(0)
	v_mfma_f32_16x16x32_bf16 v[112:115], v[200:203], v[140:143], v[112:115]
	v_mfma_f32_16x16x32_bf16 v[100:103], v[180:183], v[156:159], v[100:103]
	v_mfma_f32_16x16x32_bf16 v[96:99], v[200:203], v[156:159], v[96:99]
	v_mfma_f32_16x16x32_bf16 v[84:87], v[180:183], v[164:167], v[84:87]
	v_mfma_f32_16x16x32_bf16 v[80:83], v[200:203], v[164:167], v[80:83]
	v_mfma_f32_16x16x32_bf16 v[68:71], v[180:183], v[172:175], v[68:71]
	v_mfma_f32_16x16x32_bf16 v[64:67], v[200:203], v[172:175], v[64:67]
	s_barrier
	ds_read_b128 v[136:139], v237 offset:16384
	ds_read_b128 v[140:143], v237 offset:17408
	ds_read_b128 v[152:155], v237 offset:18432
	ds_read_b128 v[156:159], v237 offset:19456
	ds_read_b128 v[160:163], v237 offset:20480
	ds_read_b128 v[164:167], v237 offset:21504
	ds_read_b128 v[168:171], v237 offset:22528
	ds_read_b128 v[172:175], v237 offset:23552
	s_mov_b32 m0, s25
	s_nop 0
	global_load_lds_dwordx4 v188, s[56:57]
	s_add_u32 s48, s56, 0x2000
	s_addc_u32 s49, s57, 0
	s_mov_b32 m0, s28
	s_nop 0
	global_load_lds_dwordx4 v188, s[48:49]
	s_barrier
	s_waitcnt lgkmcnt(7)
	v_mfma_f32_16x16x32_bf16 v[60:63], v[120:123], v[136:139], v[60:63]
	v_mfma_f32_16x16x32_bf16 v[56:59], v[128:131], v[136:139], v[56:59]
	s_waitcnt lgkmcnt(5)
	v_mfma_f32_16x16x32_bf16 v[44:47], v[120:123], v[152:155], v[44:47]
	v_mfma_f32_16x16x32_bf16 v[40:43], v[128:131], v[152:155], v[40:43]
	s_waitcnt lgkmcnt(3)
	v_mfma_f32_16x16x32_bf16 v[28:31], v[120:123], v[160:163], v[28:31]
	v_mfma_f32_16x16x32_bf16 v[24:27], v[128:131], v[160:163], v[24:27]
	s_waitcnt lgkmcnt(1)
	v_mfma_f32_16x16x32_bf16 v[12:15], v[120:123], v[168:171], v[12:15]
	v_mfma_f32_16x16x32_bf16 v[8:11], v[128:131], v[168:171], v[8:11]
	v_mfma_f32_16x16x32_bf16 v[60:63], v[124:127], v[140:143], v[60:63]
	v_mfma_f32_16x16x32_bf16 v[56:59], v[132:135], v[140:143], v[56:59]
	v_mfma_f32_16x16x32_bf16 v[44:47], v[124:127], v[156:159], v[44:47]
	v_mfma_f32_16x16x32_bf16 v[40:43], v[132:135], v[156:159], v[40:43]
	v_mfma_f32_16x16x32_bf16 v[28:31], v[124:127], v[164:167], v[28:31]
	v_mfma_f32_16x16x32_bf16 v[24:27], v[132:135], v[164:167], v[24:27]
	s_waitcnt lgkmcnt(0)
	v_mfma_f32_16x16x32_bf16 v[12:15], v[124:127], v[172:175], v[12:15]
	v_mfma_f32_16x16x32_bf16 v[8:11], v[132:135], v[172:175], v[8:11]
	s_barrier
; #define PG8_STAGE(bufoff, gbase, hoff, imm) do { _Pragma("unroll") for (int _i = 0; _i < 2; ++_i) { \
;         asm volatile("s_mov_b32 m0, %0\n\ts_nop 0\n\tglobal_load_lds_dwordx4 %1, %2" \
;             :: "s"(lds0 + (unsigned)((bufoff) + _i * 8192)), "v"(voff0), "s"((const char*)(gbase) + (size_t)(hoff) + (size_t)(_i * 8192)) : "memory"); } } while (0)
; #define PG8_LDA(dst, b, h) do { _Pragma("unroll") for (int m = 0; m < 4; ++m) _Pragma("unroll") for (int k = 0; k < 2; ++k) dst[m][k] = *(const LAS bf16x8*)(lds + PG8_SA(b, h) + aoff + m * 2048 + k * 1024); } while (0)
; #define PG8_LDB(dst, b, h) do { _Pragma("unroll") for (int n = 0; n < 2; ++n) _Pragma("unroll") for (int k = 0; k < 2; ++k) dst[n][k] = *(const LAS bf16x8*)(lds + PG8_SB(b, h) + boff + n * 2048 + k * 1024); } while (0)
; #define PG8_MMA(ai, bj, At, Bt) do { __builtin_amdgcn_s_setprio(1); _Pragma("unroll") for (int m = 0; m < 4; ++m) _Pragma("unroll") for (int n = 0; n < 2; ++n) _Pragma("unroll") for (int k = 0; k < 2; ++k) \
;         acc[ai][bj][m][n] = __builtin_amdgcn_mfma_f32_16x16x32_bf16(Bt[n][k], At[m][k], acc[ai][bj][m][n], 0, 0, 0); __builtin_amdgcn_s_setprio(0); } while (0)
; #define PG8_WAIT_V(n) asm volatile("s_waitcnt vmcnt(" #n ")" ::: "memory")
; #define PG8_WAIT_L(n) asm volatile("s_waitcnt lgkmcnt(" #n ")" ::: "memory")
; #define PG8_BAR __builtin_amdgcn_s_barrier()
; #define PG8_SCHED __builtin_amdgcn_sched_barrier(0)
; template <class Epi>
; __device__ __forceinline__ void gemm_phase(LAS unsigned char* lds, const Gemm g, const StaticOrder& S, const Epi& E) {
;     ...
;             PG8_STAGE(PG8_SB(0, 1), b2, hB, 0);
;             PG8_WAIT_V(6); PG8_BAR; PG8_MMA(1, 1, At, B1); PG8_BAR;
;             PG8_LDB(B0, 1, 0); PG8_SCHED; PG8_LDA(At, 1, 0); PG8_STAGE(PG8_SA(0, 1), a2, hA, 0);
;             PG8_WAIT_L(8); PG8_BAR; PG8_WAIT_L(0); PG8_MMA(0, 0, At, B0); PG8_BAR; PG8_SCHED;
;             PG8_LDB(B1, 1, 1); PG8_STAGE(PG8_SB(1, 0), b2 + KS, 0, 0);
;             PG8_BAR; PG8_WAIT_L(0); PG8_MMA(0, 1, At, B1); PG8_BAR;
;             PG8_LDA(At, 1, 1); PG8_STAGE(PG8_SA(1, 0), a2 + KS, 0, 0);
;             PG8_BAR; PG8_WAIT_L(0); PG8_MMA(1, 0, At, B0); PG8_BAR; PG8_SCHED;
	s_add_u32 s48, s60, 0x160000
	s_addc_u32 s49, s61, 0
	s_mov_b32 m0, s29
	s_nop 0
	global_load_lds_dwordx4 v188, s[48:49]
	s_add_u32 s48, s60, 0x162000
	s_addc_u32 s49, s61, 0
	s_mov_b32 m0, s30
	s_nop 0
	global_load_lds_dwordx4 v188, s[48:49]
	s_waitcnt vmcnt(10)
	s_barrier
	v_mfma_f32_16x16x32_bf16 v[52:55], v[176:179], v[136:139], v[52:55]
	v_mfma_f32_16x16x32_bf16 v[48:51], v[184:187], v[136:139], v[48:51]
	v_mfma_f32_16x16x32_bf16 v[36:39], v[176:179], v[152:155], v[36:39]
	v_mfma_f32_16x16x32_bf16 v[32:35], v[184:187], v[152:155], v[32:35]
	v_mfma_f32_16x16x32_bf16 v[20:23], v[176:179], v[160:163], v[20:23]
	v_mfma_f32_16x16x32_bf16 v[16:19], v[184:187], v[160:163], v[16:19]
	v_mfma_f32_16x16x32_bf16 v[4:7], v[176:179], v[168:171], v[4:7]
	v_mfma_f32_16x16x32_bf16 v[0:3], v[184:187], v[168:171], v[0:3]
	v_mfma_f32_16x16x32_bf16 v[52:55], v[180:183], v[140:143], v[52:55]
	v_mfma_f32_16x16x32_bf16 v[48:51], v[200:203], v[140:143], v[48:51]
	v_mfma_f32_16x16x32_bf16 v[36:39], v[180:183], v[156:159], v[36:39]
	v_mfma_f32_16x16x32_bf16 v[32:35], v[200:203], v[156:159], v[32:35]
	v_mfma_f32_16x16x32_bf16 v[20:23], v[180:183], v[164:167], v[20:23]
	v_mfma_f32_16x16x32_bf16 v[16:19], v[200:203], v[164:167], v[16:19]
	v_mfma_f32_16x16x32_bf16 v[4:7], v[180:183], v[172:175], v[4:7]
	v_mfma_f32_16x16x32_bf16 v[0:3], v[200:203], v[172:175], v[0:3]
	v_add_u32_e32 v132, 0x18000, v236
	s_barrier
	ds_read_b128 v[120:123], v132
	ds_read_b128 v[124:127], v132 offset:1024
	ds_read_b128 v[128:131], v132 offset:2048
	ds_read_b128 v[132:135], v132 offset:3072
	ds_read_b128 v[136:139], v237 offset:32768
	ds_read_b128 v[140:143], v237 offset:33792
	ds_read_b128 v[152:155], v237 offset:34816
	ds_read_b128 v[156:159], v237 offset:35840
	ds_read_b128 v[160:163], v237 offset:36864
	ds_read_b128 v[164:167], v237 offset:37888
	ds_read_b128 v[168:171], v237 offset:38912
	ds_read_b128 v[172:175], v237 offset:39936
	s_add_u32 s48, s56, 0x160000
	s_addc_u32 s49, s57, 0
	s_mov_b32 m0, s34
	s_nop 0
	global_load_lds_dwordx4 v188, s[48:49]
	s_add_u32 s48, s56, 0x162000
	s_addc_u32 s49, s57, 0
	s_mov_b32 m0, s37
	s_nop 0
	global_load_lds_dwordx4 v188, s[48:49]
	s_waitcnt lgkmcnt(8)
	s_waitcnt vmcnt(10)
	s_barrier
	s_waitcnt lgkmcnt(7)
	v_mfma_f32_16x16x32_bf16 v[148:151], v[120:123], v[136:139], v[148:151]
	v_mfma_f32_16x16x32_bf16 v[144:147], v[128:131], v[136:139], v[144:147]
	s_waitcnt lgkmcnt(5)
	v_mfma_f32_16x16x32_bf16 v[108:111], v[120:123], v[152:155], v[108:111]
	v_mfma_f32_16x16x32_bf16 v[104:107], v[128:131], v[152:155], v[104:107]
	s_waitcnt lgkmcnt(3)
	v_mfma_f32_16x16x32_bf16 v[92:95], v[120:123], v[160:163], v[92:95]
	v_mfma_f32_16x16x32_bf16 v[88:91], v[128:131], v[160:163], v[88:91]
	s_waitcnt lgkmcnt(1)
	v_mfma_f32_16x16x32_bf16 v[76:79], v[120:123], v[168:171], v[76:79]
	v_mfma_f32_16x16x32_bf16 v[72:75], v[128:131], v[168:171], v[72:75]
	v_mfma_f32_16x16x32_bf16 v[148:151], v[124:127], v[140:143], v[148:151]
	v_mfma_f32_16x16x32_bf16 v[144:147], v[132:135], v[140:143], v[144:147]
	v_mfma_f32_16x16x32_bf16 v[108:111], v[124:127], v[156:159], v[108:111]
	v_mfma_f32_16x16x32_bf16 v[104:107], v[132:135], v[156:159], v[104:107]
	v_mfma_f32_16x16x32_bf16 v[92:95], v[124:127], v[164:167], v[92:95]
	v_mfma_f32_16x16x32_bf16 v[88:91], v[132:135], v[164:167], v[88:91]
	s_waitcnt lgkmcnt(0)
	v_mfma_f32_16x16x32_bf16 v[76:79], v[124:127], v[172:175], v[76:79]
	v_mfma_f32_16x16x32_bf16 v[72:75], v[132:135], v[172:175], v[72:75]
	s_barrier
	v_add_u32_e32 v200, 0x1c000, v236
	ds_read_b128 v[176:179], v200
	ds_read_b128 v[180:183], v200 offset:1024
	ds_read_b128 v[184:187], v200 offset:2048
	ds_read_b128 v[200:203], v200 offset:3072
	s_add_u32 s48, s60, 0x4000
	s_addc_u32 s49, s61, 0
	s_mov_b32 m0, s41
	s_nop 0
	global_load_lds_dwordx4 v188, s[48:49]
	s_add_u32 s48, s60, 0x6000
	s_addc_u32 s49, s61, 0
	s_mov_b32 m0, s42
	s_nop 0
	global_load_lds_dwordx4 v188, s[48:49]
	s_waitcnt vmcnt(10)
	s_barrier
	s_waitcnt lgkmcnt(3)
	v_mfma_f32_16x16x32_bf16 v[116:119], v[176:179], v[136:139], v[116:119]
	s_waitcnt lgkmcnt(1)
	v_mfma_f32_16x16x32_bf16 v[112:115], v[184:187], v[136:139], v[112:115]
	v_mfma_f32_16x16x32_bf16 v[100:103], v[176:179], v[152:155], v[100:103]
	v_mfma_f32_16x16x32_bf16 v[96:99], v[184:187], v[152:155], v[96:99]
	v_mfma_f32_16x16x32_bf16 v[84:87], v[176:179], v[160:163], v[84:87]
	v_mfma_f32_16x16x32_bf16 v[80:83], v[184:187], v[160:163], v[80:83]
	v_mfma_f32_16x16x32_bf16 v[68:71], v[176:179], v[168:171], v[68:71]
	v_mfma_f32_16x16x32_bf16 v[64:67], v[184:187], v[168:171], v[64:67]
	v_mfma_f32_16x16x32_bf16 v[116:119], v[180:183], v[140:143], v[116:119]
	s_waitcnt lgkmcnt(0)
	v_mfma_f32_16x16x32_bf16 v[112:115], v[200:203], v[140:143], v[112:115]
	v_mfma_f32_16x16x32_bf16 v[100:103], v[180:183], v[156:159], v[100:103]
	v_mfma_f32_16x16x32_bf16 v[96:99], v[200:203], v[156:159], v[96:99]
	v_mfma_f32_16x16x32_bf16 v[84:87], v[180:183], v[164:167], v[84:87]
	v_mfma_f32_16x16x32_bf16 v[80:83], v[200:203], v[164:167], v[80:83]
	v_mfma_f32_16x16x32_bf16 v[68:71], v[180:183], v[172:175], v[68:71]
	v_mfma_f32_16x16x32_bf16 v[64:67], v[200:203], v[172:175], v[64:67]
	s_barrier
	ds_read_b128 v[136:139], v237 offset:49152
	ds_read_b128 v[140:143], v237 offset:50176
	ds_read_b128 v[152:155], v237 offset:51200
	ds_read_b128 v[156:159], v237 offset:52224
	ds_read_b128 v[160:163], v237 offset:53248
	ds_read_b128 v[164:167], v237 offset:54272
	ds_read_b128 v[168:171], v237 offset:55296
	ds_read_b128 v[172:175], v237 offset:56320
	s_add_u32 s48, s56, 0x4000
	s_addc_u32 s49, s57, 0
	s_mov_b32 m0, s43
	s_nop 0
	global_load_lds_dwordx4 v188, s[48:49]
	s_add_u32 s48, s56, 0x6000
	s_addc_u32 s49, s57, 0
	s_mov_b32 m0, s62
	s_nop 0
	global_load_lds_dwordx4 v188, s[48:49]
	s_barrier
; template <class Epi>
; __device__ __forceinline__ void gemm_phase(LAS unsigned char* lds, const Gemm g, const StaticOrder& S, const Epi& E) {
;     ...
;             PG8_BAR; PG8_WAIT_L(0); PG8_MMA(1, 0, At, B0); PG8_BAR; PG8_SCHED;
;             PG8_STAGE(PG8_SB(1, 1), b2 + KS, hB, 0);
;             PG8_WAIT_V(6); PG8_BAR; PG8_MMA(1, 1, At, B1); PG8_BAR;
;     __device__ __forceinline__ void operator()(f32x4 (&acc)[2][2][4][2], const Unit& u, int wr, int wc, int fr, int fq, LAS unsigned char*) const {
;         const int b = u.pm >> 6;
;         const int col0 = u.pn * BM + wc * 32 + 8 * fq;
;         const size_t off0 = (size_t)(u.pm * BM + wr * 64 + fr) * D + col0;
;         f32x4 sc[2][2];
; #pragma unroll
;         for (int bj = 0; bj < 2; ++bj)
; #pragma unroll
;             for (int n = 0; n < 2; ++n) { f32x4 gt = *(const f32x4*)(gate + (size_t)b * MODW + col0 + bj * HALF + n * 4); sc[bj][n] = gt + 1.0f;
;                 if (cs) sc[bj][n] *= *(const f32x4*)(cs + col0 + bj * HALF + n * 4); }
;         if (IN_F32) {
; #pragma unroll
;             for (int ai = 0; ai < 2; ++ai) {
;                 f32x4 r[4][2][2];
; #pragma unroll
;                 for (int m = 0; m < 4; ++m)
; #pragma unroll
;                     for (int bj = 0; bj < 2; ++bj)
; #pragma unroll
;                         for (int n = 0; n < 2; ++n) r[m][bj][n] = *(const f32x4*)((const float*)in + off0 + (size_t)(ai * HALF + m * 16) * D + bj * HALF + n * 4);
; #pragma unroll
;                 for (int m = 0; m < 4; ++m)
; #pragma unroll
;                     for (int bj = 0; bj < 2; ++bj) { const f32x4 r0 = r[m][bj][0] + sc[bj][0] * acc[ai][bj][m][0], r1 = r[m][bj][1] + sc[bj][1] * acc[ai][bj][m][1];
;                         u32x4 w; w.x = cvt_pk_bf16(r0[0], r0[1]); w.y = cvt_pk_bf16(r0[2], r0[3]); w.z = cvt_pk_bf16(r1[0], r1[1]); w.w = cvt_pk_bf16(r1[2], r1[3]);
;                         *(u32x4*)(out + off0 + (size_t)(ai * HALF + m * 16) * D + bj * HALF) = w; }
;                 asm volatile("" ::: "memory");
;             }
;         } else {
;             u32x4 xb[2][4][2];
; #pragma unroll
;             for (int ai = 0; ai < 2; ++ai)
; #pragma unroll
;                 for (int m = 0; m < 4; ++m)
; #pragma unroll
;                     for (int bj = 0; bj < 2; ++bj) xb[ai][m][bj] = *(const u32x4*)((const bf16_t*)in + off0 + (size_t)(ai * HALF + m * 16) * D + bj * HALF);
; #pragma unroll
	s_waitcnt lgkmcnt(7)
	v_mfma_f32_16x16x32_bf16 v[60:63], v[120:123], v[136:139], v[60:63]
	v_mfma_f32_16x16x32_bf16 v[56:59], v[128:131], v[136:139], v[56:59]
	s_waitcnt lgkmcnt(5)
	v_mfma_f32_16x16x32_bf16 v[44:47], v[120:123], v[152:155], v[44:47]
	v_mfma_f32_16x16x32_bf16 v[40:43], v[128:131], v[152:155], v[40:43]
	s_waitcnt lgkmcnt(3)
	v_mfma_f32_16x16x32_bf16 v[28:31], v[120:123], v[160:163], v[28:31]
	v_mfma_f32_16x16x32_bf16 v[24:27], v[128:131], v[160:163], v[24:27]
	s_waitcnt lgkmcnt(1)
	v_mfma_f32_16x16x32_bf16 v[12:15], v[120:123], v[168:171], v[12:15]
	v_mfma_f32_16x16x32_bf16 v[8:11], v[128:131], v[168:171], v[8:11]
	v_mfma_f32_16x16x32_bf16 v[60:63], v[124:127], v[140:143], v[60:63]
	v_mfma_f32_16x16x32_bf16 v[56:59], v[132:135], v[140:143], v[56:59]
	v_mfma_f32_16x16x32_bf16 v[44:47], v[124:127], v[156:159], v[44:47]
	v_mfma_f32_16x16x32_bf16 v[40:43], v[132:135], v[156:159], v[40:43]
	v_mfma_f32_16x16x32_bf16 v[28:31], v[124:127], v[164:167], v[28:31]
	v_mfma_f32_16x16x32_bf16 v[24:27], v[132:135], v[164:167], v[24:27]
	s_waitcnt lgkmcnt(0)
	v_mfma_f32_16x16x32_bf16 v[12:15], v[124:127], v[172:175], v[12:15]
	v_mfma_f32_16x16x32_bf16 v[8:11], v[132:135], v[172:175], v[8:11]
	s_barrier
	s_add_u32 s48, s60, 0x164000
	s_addc_u32 s49, s61, 0
	s_mov_b32 m0, s63
	s_nop 0
	global_load_lds_dwordx4 v188, s[48:49]
	s_add_u32 s48, s60, 0x166000
	s_addc_u32 s49, s61, 0
	s_mov_b32 m0, s64
	s_nop 0
	global_load_lds_dwordx4 v188, s[48:49]
	s_waitcnt vmcnt(10)
	s_barrier
	v_mfma_f32_16x16x32_bf16 v[52:55], v[176:179], v[136:139], v[52:55]
	v_mfma_f32_16x16x32_bf16 v[48:51], v[184:187], v[136:139], v[48:51]
	v_mfma_f32_16x16x32_bf16 v[36:39], v[176:179], v[152:155], v[36:39]
	v_mfma_f32_16x16x32_bf16 v[32:35], v[184:187], v[152:155], v[32:35]
	v_mfma_f32_16x16x32_bf16 v[20:23], v[176:179], v[160:163], v[20:23]
	v_mfma_f32_16x16x32_bf16 v[16:19], v[184:187], v[160:163], v[16:19]
	v_mfma_f32_16x16x32_bf16 v[4:7], v[176:179], v[168:171], v[4:7]
	v_mfma_f32_16x16x32_bf16 v[0:3], v[184:187], v[168:171], v[0:3]
	v_mfma_f32_16x16x32_bf16 v[52:55], v[180:183], v[140:143], v[52:55]
	v_mfma_f32_16x16x32_bf16 v[48:51], v[200:203], v[140:143], v[48:51]
	v_mfma_f32_16x16x32_bf16 v[36:39], v[180:183], v[156:159], v[36:39]
	v_mfma_f32_16x16x32_bf16 v[32:35], v[200:203], v[156:159], v[32:35]
	v_mfma_f32_16x16x32_bf16 v[20:23], v[180:183], v[164:167], v[20:23]
	v_mfma_f32_16x16x32_bf16 v[16:19], v[200:203], v[164:167], v[16:19]
	v_mfma_f32_16x16x32_bf16 v[4:7], v[180:183], v[172:175], v[4:7]
	v_mfma_f32_16x16x32_bf16 v[0:3], v[200:203], v[172:175], v[0:3]
	s_add_i32 s69, s69, 2
	s_add_u32 s0, s0, 0x8000
	s_addc_u32 s1, s1, 0
	s_cmpk_gt_u32 s69, 0x55
	s_mov_b64 s[56:57], s[58:59]
	s_barrier
	s_cbranch_scc0 .LBB0_860
	s_ashr_i32 s0, s50, 6
	s_mul_hi_i32 s1, s0, 0xc000
	s_mul_i32 s0, s0, 0xc000
	v_lshl_or_b32 v128, s51, 8, v234
	s_add_u32 s0, s39, s0
	v_ashrrev_i32_e32 v129, 31, v128
	s_addc_u32 s1, s40, s1
	v_lshl_add_u64 v[130:131], v[128:129], 2, s[0:1]
	global_load_dwordx4 v[208:211], v[130:131], off offset:16
	global_load_dwordx4 v[212:215], v[130:131], off
	global_load_dwordx4 v[200:203], v[130:131], off offset:528
	global_load_dwordx4 v[204:207], v[130:131], off offset:512
	s_mov_b32 s51, s67
	s_mov_b64 s[58:59], s[8:9]
	s_mov_b64 s[56:57], s[6:7]
	v_lshl_add_u32 v120, s50, 8, v233
	v_ashrrev_i32_e32 v121, 31, v120
	v_lshlrev_b64 v[120:121], 11, v[120:121]
	v_lshl_add_u64 v[120:121], v[120:121], 0, v[128:129]
	v_lshlrev_b64 v[216:217], 1, v[120:121]
	v_lshl_add_u64 v[120:121], s[52:53], 0, v[216:217]
	global_load_dwordx4 v[238:241], v[120:121], off
	global_load_dwordx4 v[184:187], v[120:121], off offset:256
	v_add_co_u32_e32 v122, vcc, s45, v120
	s_nop 1
	v_addc_co_u32_e32 v123, vcc, 0, v121, vcc
	global_load_dwordx4 v[180:183], v[122:123], off
	global_load_dwordx4 v[176:179], v[122:123], off offset:256
	v_add_co_u32_e32 v122, vcc, s36, v120
	s_nop 0
	s_nop 0
	v_addc_co_u32_e32 v123, vcc, 0, v121, vcc
	global_load_dwordx4 v[172:175], v[122:123], off
	global_load_dwordx4 v[168:171], v[122:123], off offset:256
	v_add_co_u32_e32 v122, vcc, s23, v120
	s_mov_b32 s50, s68
	s_nop 0
	v_addc_co_u32_e32 v123, vcc, 0, v121, vcc
	global_load_dwordx4 v[164:167], v[122:123], off
	global_load_dwordx4 v[160:163], v[122:123], off offset:256
	v_add_co_u32_e32 v122, vcc, s93, v120
	s_waitcnt vmcnt(7)
	v_pk_add_f32 v[200:201], v[200:201], 1.0 op_sel_hi:[1,0]
	v_pk_add_f32 v[202:203], v[202:203], 1.0 op_sel_hi:[1,0]
	v_pk_add_f32 v[204:205], v[204:205], 1.0 op_sel_hi:[1,0]
	v_pk_add_f32 v[206:207], v[206:207], 1.0 op_sel_hi:[1,0]
	v_pk_add_f32 v[208:209], v[208:209], 1.0 op_sel_hi:[1,0]
	v_pk_add_f32 v[210:211], v[210:211], 1.0 op_sel_hi:[1,0]
	v_pk_add_f32 v[212:213], v[212:213], 1.0 op_sel_hi:[1,0]
	v_pk_add_f32 v[214:215], v[214:215], 1.0 op_sel_hi:[1,0]
	v_lshlrev_b32_e32 v230, 16, v238
	v_addc_co_u32_e32 v123, vcc, 0, v121, vcc
	global_load_dwordx4 v[156:159], v[122:123], off
	global_load_dwordx4 v[152:155], v[122:123], off offset:256
	v_add_co_u32_e32 v122, vcc, s33, v120
	v_and_b32_e32 v231, 0xffff0000, v238
	s_nop 0
	v_addc_co_u32_e32 v123, vcc, 0, v121, vcc
	global_load_dwordx4 v[140:143], v[122:123], off
	global_load_dwordx4 v[136:139], v[122:123], off offset:256
	v_add_co_u32_e32 v122, vcc, s18, v120
	v_lshlrev_b32_e32 v242, 16, v240
	s_nop 0
	v_addc_co_u32_e32 v123, vcc, 0, v121, vcc
	global_load_dwordx4 v[132:135], v[122:123], off
	global_load_dwordx4 v[128:131], v[122:123], off offset:256
	v_add_co_u32_e32 v120, vcc, s19, v120
	v_and_b32_e32 v243, 0xffff0000, v240
	s_nop 0
	v_addc_co_u32_e32 v121, vcc, 0, v121, vcc
	global_load_dwordx4 v[124:127], v[120:121], off
	s_nop 0
	global_load_dwordx4 v[120:123], v[120:121], off offset:256
	v_lshlrev_b32_e32 v238, 16, v239
	v_and_b32_e32 v239, 0xffff0000, v239
	v_lshlrev_b32_e32 v240, 16, v241
	v_and_b32_e32 v241, 0xffff0000, v241
	v_pk_fma_f32 v[148:149], v[148:149], v[212:213], v[230:231]
	v_pk_fma_f32 v[144:145], v[144:145], v[208:209], v[242:243]
	v_pk_fma_f32 v[150:151], v[150:151], v[214:215], v[238:239]
	v_pk_fma_f32 v[230:231], v[146:147], v[210:211], v[240:241]
	v_cvt_pk_bf16_f32 v146, v148, v149
	v_cvt_pk_bf16_f32 v147, v150, v151
	v_cvt_pk_bf16_f32 v148, v144, v145
	v_lshl_add_u64 v[144:145], s[54:55], 0, v[216:217]
	v_cvt_pk_bf16_f32 v149, v230, v231
	global_store_dwordx4 v[144:145], v[146:149], off
	s_waitcnt vmcnt(15)
; __device__ __forceinline__ unsigned cvt_pk_bf16(float lo, float hi) { unsigned r; asm volatile("v_cvt_pk_bf16_f32 %0, %1, %2" : "=v"(r) : "v"(lo), "v"(hi)); return r; }
;     __device__ __forceinline__ void operator()(f32x4 (&acc)[2][2][4][2], const Unit& u, int wr, int wc, int fr, int fq, LAS unsigned char*) const {
;     ...
; #pragma unroll
;             for (int ai = 0; ai < 2; ++ai)
; #pragma unroll
;                 for (int m = 0; m < 4; ++m)
; #pragma unroll
;                     for (int bj = 0; bj < 2; ++bj) { const u32x4 x = xb[ai][m][bj];
;                         f32x4 r0 = (f32x4){__uint_as_float(x.x << 16), __uint_as_float(x.x & 0xffff0000u), __uint_as_float(x.y << 16), __uint_as_float(x.y & 0xffff0000u)};
;                         f32x4 r1 = (f32x4){__uint_as_float(x.z << 16), __uint_as_float(x.z & 0xffff0000u), __uint_as_float(x.w << 16), __uint_as_float(x.w & 0xffff0000u)};
;                         r0 += sc[bj][0] * acc[ai][bj][m][0]; r1 += sc[bj][1] * acc[ai][bj][m][1];
;                         u32x4 w; w.x = cvt_pk_bf16(r0[0], r0[1]); w.y = cvt_pk_bf16(r0[2], r0[3]); w.z = cvt_pk_bf16(r1[0], r1[1]); w.w = cvt_pk_bf16(r1[2], r1[3]);
;                         *(u32x4*)(out + off0 + (size_t)(ai * HALF + m * 16) * D + bj * HALF) = w; }
	v_lshlrev_b32_e32 v150, 16, v186
	v_and_b32_e32 v151, 0xffff0000, v186
	v_lshlrev_b32_e32 v146, 16, v184
	v_and_b32_e32 v147, 0xffff0000, v184
	v_lshlrev_b32_e32 v148, 16, v185
	v_and_b32_e32 v149, 0xffff0000, v185
	v_lshlrev_b32_e32 v184, 16, v187
	v_and_b32_e32 v185, 0xffff0000, v187
	v_pk_fma_f32 v[118:119], v[118:119], v[206:207], v[148:149]
	v_pk_fma_f32 v[116:117], v[116:117], v[204:205], v[146:147]
	v_pk_fma_f32 v[146:147], v[114:115], v[202:203], v[184:185]
	v_pk_fma_f32 v[114:115], v[112:113], v[200:201], v[150:151]
	v_cvt_pk_bf16_f32 v112, v116, v117
	v_cvt_pk_bf16_f32 v113, v118, v119
	s_waitcnt vmcnt(14)
	v_lshlrev_b32_e32 v116, 16, v182
	v_cvt_pk_bf16_f32 v114, v114, v115
	v_cvt_pk_bf16_f32 v115, v146, v147
	global_store_dwordx4 v[144:145], v[112:115], off offset:256
	v_and_b32_e32 v117, 0xffff0000, v182
	v_lshlrev_b32_e32 v118, 16, v183
	v_lshlrev_b32_e32 v112, 16, v180
	v_and_b32_e32 v113, 0xffff0000, v180
	v_and_b32_e32 v119, 0xffff0000, v183
	v_pk_fma_f32 v[108:109], v[108:109], v[212:213], v[112:113]
	v_lshlrev_b32_e32 v114, 16, v181
	v_and_b32_e32 v115, 0xffff0000, v181
	v_pk_fma_f32 v[112:113], v[106:107], v[210:211], v[118:119]
	v_pk_fma_f32 v[106:107], v[104:105], v[208:209], v[116:117]
	v_cvt_pk_bf16_f32 v104, v108, v109
	v_add_co_u32_e32 v108, vcc, s45, v144
	v_pk_fma_f32 v[110:111], v[110:111], v[214:215], v[114:115]
	s_nop 0
	v_addc_co_u32_e32 v109, vcc, 0, v145, vcc
	v_cvt_pk_bf16_f32 v105, v110, v111
	v_cvt_pk_bf16_f32 v106, v106, v107
	v_cvt_pk_bf16_f32 v107, v112, v113
	global_store_dwordx4 v[108:109], v[104:107], off
	s_waitcnt vmcnt(15)
	v_lshlrev_b32_e32 v110, 16, v178
	v_and_b32_e32 v111, 0xffff0000, v178
	v_lshlrev_b32_e32 v104, 16, v176
	v_and_b32_e32 v105, 0xffff0000, v176
	v_lshlrev_b32_e32 v106, 16, v177
	v_and_b32_e32 v107, 0xffff0000, v177
	v_lshlrev_b32_e32 v112, 16, v179
	v_and_b32_e32 v113, 0xffff0000, v179
	v_pk_fma_f32 v[102:103], v[102:103], v[206:207], v[106:107]
	v_pk_fma_f32 v[100:101], v[100:101], v[204:205], v[104:105]
	v_pk_fma_f32 v[104:105], v[98:99], v[202:203], v[112:113]
	v_pk_fma_f32 v[98:99], v[96:97], v[200:201], v[110:111]
	v_cvt_pk_bf16_f32 v96, v100, v101
	v_cvt_pk_bf16_f32 v97, v102, v103
	s_waitcnt vmcnt(14)
	v_lshlrev_b32_e32 v100, 16, v174
	v_cvt_pk_bf16_f32 v98, v98, v99
	v_cvt_pk_bf16_f32 v99, v104, v105
	global_store_dwordx4 v[108:109], v[96:99], off offset:256
	v_and_b32_e32 v101, 0xffff0000, v174
	v_lshlrev_b32_e32 v102, 16, v175
	v_lshlrev_b32_e32 v96, 16, v172
	v_and_b32_e32 v97, 0xffff0000, v172
	v_and_b32_e32 v103, 0xffff0000, v175
	v_pk_fma_f32 v[92:93], v[92:93], v[212:213], v[96:97]
	v_lshlrev_b32_e32 v98, 16, v173
	v_and_b32_e32 v99, 0xffff0000, v173
	v_pk_fma_f32 v[96:97], v[90:91], v[210:211], v[102:103]
	v_pk_fma_f32 v[90:91], v[88:89], v[208:209], v[100:101]
	v_cvt_pk_bf16_f32 v88, v92, v93
	v_add_co_u32_e32 v92, vcc, s36, v144
	v_pk_fma_f32 v[94:95], v[94:95], v[214:215], v[98:99]
	s_nop 0
	v_addc_co_u32_e32 v93, vcc, 0, v145, vcc
	v_cvt_pk_bf16_f32 v89, v94, v95
	v_cvt_pk_bf16_f32 v90, v90, v91
	v_cvt_pk_bf16_f32 v91, v96, v97
	global_store_dwordx4 v[92:93], v[88:91], off
	s_waitcnt vmcnt(15)
	v_lshlrev_b32_e32 v94, 16, v170
	v_and_b32_e32 v95, 0xffff0000, v170
	v_lshlrev_b32_e32 v88, 16, v168
	v_and_b32_e32 v89, 0xffff0000, v168
	v_lshlrev_b32_e32 v90, 16, v169
	v_and_b32_e32 v91, 0xffff0000, v169
	v_lshlrev_b32_e32 v96, 16, v171
	v_and_b32_e32 v97, 0xffff0000, v171
	v_pk_fma_f32 v[86:87], v[86:87], v[206:207], v[90:91]
	v_pk_fma_f32 v[84:85], v[84:85], v[204:205], v[88:89]
	v_pk_fma_f32 v[88:89], v[82:83], v[202:203], v[96:97]
	v_pk_fma_f32 v[82:83], v[80:81], v[200:201], v[94:95]
	v_cvt_pk_bf16_f32 v80, v84, v85
	v_cvt_pk_bf16_f32 v81, v86, v87
	s_waitcnt vmcnt(14)
	v_lshlrev_b32_e32 v84, 16, v166
	v_cvt_pk_bf16_f32 v82, v82, v83
	v_cvt_pk_bf16_f32 v83, v88, v89
	global_store_dwordx4 v[92:93], v[80:83], off offset:256
	v_and_b32_e32 v85, 0xffff0000, v166
	v_lshlrev_b32_e32 v86, 16, v167
	v_lshlrev_b32_e32 v80, 16, v164
	v_and_b32_e32 v81, 0xffff0000, v164
	v_and_b32_e32 v87, 0xffff0000, v167
	v_pk_fma_f32 v[76:77], v[76:77], v[212:213], v[80:81]
	v_lshlrev_b32_e32 v82, 16, v165
	v_and_b32_e32 v83, 0xffff0000, v165
	v_pk_fma_f32 v[80:81], v[74:75], v[210:211], v[86:87]
	v_pk_fma_f32 v[74:75], v[72:73], v[208:209], v[84:85]
	v_cvt_pk_bf16_f32 v72, v76, v77
	v_add_co_u32_e32 v76, vcc, s23, v144
	v_pk_fma_f32 v[78:79], v[78:79], v[214:215], v[82:83]
	s_nop 0
	v_addc_co_u32_e32 v77, vcc, 0, v145, vcc
	v_cvt_pk_bf16_f32 v73, v78, v79
	v_cvt_pk_bf16_f32 v74, v74, v75
	v_cvt_pk_bf16_f32 v75, v80, v81
	global_store_dwordx4 v[76:77], v[72:75], off
	s_waitcnt vmcnt(15)
	v_lshlrev_b32_e32 v78, 16, v162
	v_and_b32_e32 v79, 0xffff0000, v162
	v_lshlrev_b32_e32 v72, 16, v160
	v_and_b32_e32 v73, 0xffff0000, v160
	v_lshlrev_b32_e32 v74, 16, v161
	v_and_b32_e32 v75, 0xffff0000, v161
	v_lshlrev_b32_e32 v80, 16, v163
	v_and_b32_e32 v81, 0xffff0000, v163
	v_pk_fma_f32 v[70:71], v[70:71], v[206:207], v[74:75]
	v_pk_fma_f32 v[68:69], v[68:69], v[204:205], v[72:73]
	v_pk_fma_f32 v[72:73], v[66:67], v[202:203], v[80:81]
	v_pk_fma_f32 v[66:67], v[64:65], v[200:201], v[78:79]
	v_cvt_pk_bf16_f32 v64, v68, v69
	v_cvt_pk_bf16_f32 v65, v70, v71
	s_waitcnt vmcnt(14)
; __device__ __forceinline__ unsigned cvt_pk_bf16(float lo, float hi) { unsigned r; asm volatile("v_cvt_pk_bf16_f32 %0, %1, %2" : "=v"(r) : "v"(lo), "v"(hi)); return r; }
; #define PG8_WAIT_V(n) asm volatile("s_waitcnt vmcnt(" #n ")" ::: "memory")
; #define PG8_BAR __builtin_amdgcn_s_barrier()
; template <class Epi>
; __device__ __forceinline__ void gemm_phase(LAS unsigned char* lds, const Gemm g, const StaticOrder& S, const Epi& E) {
;     ...
;         if (!has_next) break;
; #pragma unroll
;         for (int a = 0; a < 2; ++a)
; #pragma unroll
;             for (int b = 0; b < 2; ++b)
; #pragma unroll
;                 for (int m = 0; m < 4; ++m)
; #pragma unroll
;                     for (int n = 0; n < 2; ++n) acc[a][b][m][n] = (f32x4){0.f, 0.f, 0.f, 0.f};
;         cur = nxt; cA = nA; cB = nB; ++ui;
;     }
;     PG8_WAIT_V(0);
;     if (wr == 0) PG8_BAR;
;     PG8_BAR;
;     __device__ __forceinline__ void operator()(f32x4 (&acc)[2][2][4][2], const Unit& u, int wr, int wc, int fr, int fq, LAS unsigned char*) const {
;     ...
; #pragma unroll
;             for (int ai = 0; ai < 2; ++ai)
; #pragma unroll
;                 for (int m = 0; m < 4; ++m)
; #pragma unroll
;                     for (int bj = 0; bj < 2; ++bj) { const u32x4 x = xb[ai][m][bj];
;                         f32x4 r0 = (f32x4){__uint_as_float(x.x << 16), __uint_as_float(x.x & 0xffff0000u), __uint_as_float(x.y << 16), __uint_as_float(x.y & 0xffff0000u)};
;                         f32x4 r1 = (f32x4){__uint_as_float(x.z << 16), __uint_as_float(x.z & 0xffff0000u), __uint_as_float(x.w << 16), __uint_as_float(x.w & 0xffff0000u)};
;                         r0 += sc[bj][0] * acc[ai][bj][m][0]; r1 += sc[bj][1] * acc[ai][bj][m][1];
;                         u32x4 w; w.x = cvt_pk_bf16(r0[0], r0[1]); w.y = cvt_pk_bf16(r0[2], r0[3]); w.z = cvt_pk_bf16(r1[0], r1[1]); w.w = cvt_pk_bf16(r1[2], r1[3]);
;                         *(u32x4*)(out + off0 + (size_t)(ai * HALF + m * 16) * D + bj * HALF) = w; }
	v_lshlrev_b32_e32 v68, 16, v158
	v_cvt_pk_bf16_f32 v66, v66, v67
	v_cvt_pk_bf16_f32 v67, v72, v73
	global_store_dwordx4 v[76:77], v[64:67], off offset:256
	v_and_b32_e32 v69, 0xffff0000, v158
	v_lshlrev_b32_e32 v70, 16, v159
	v_lshlrev_b32_e32 v64, 16, v156
	v_and_b32_e32 v65, 0xffff0000, v156
	v_and_b32_e32 v71, 0xffff0000, v159
	v_pk_fma_f32 v[60:61], v[60:61], v[212:213], v[64:65]
	v_lshlrev_b32_e32 v66, 16, v157
	v_and_b32_e32 v67, 0xffff0000, v157
	v_pk_fma_f32 v[64:65], v[58:59], v[210:211], v[70:71]
	v_pk_fma_f32 v[58:59], v[56:57], v[208:209], v[68:69]
	v_cvt_pk_bf16_f32 v56, v60, v61
	v_add_co_u32_e32 v60, vcc, s93, v144
	v_pk_fma_f32 v[62:63], v[62:63], v[214:215], v[66:67]
	s_nop 0
	v_addc_co_u32_e32 v61, vcc, 0, v145, vcc
	v_cvt_pk_bf16_f32 v57, v62, v63
	v_cvt_pk_bf16_f32 v58, v58, v59
	v_cvt_pk_bf16_f32 v59, v64, v65
	global_store_dwordx4 v[60:61], v[56:59], off
	s_waitcnt vmcnt(15)
	v_lshlrev_b32_e32 v62, 16, v154
	v_and_b32_e32 v63, 0xffff0000, v154
	v_lshlrev_b32_e32 v56, 16, v152
	v_and_b32_e32 v57, 0xffff0000, v152
	v_lshlrev_b32_e32 v58, 16, v153
	v_and_b32_e32 v59, 0xffff0000, v153
	v_lshlrev_b32_e32 v64, 16, v155
	v_and_b32_e32 v65, 0xffff0000, v155
	v_pk_fma_f32 v[54:55], v[54:55], v[206:207], v[58:59]
	v_pk_fma_f32 v[52:53], v[52:53], v[204:205], v[56:57]
	v_pk_fma_f32 v[56:57], v[50:51], v[202:203], v[64:65]
	v_pk_fma_f32 v[50:51], v[48:49], v[200:201], v[62:63]
	v_cvt_pk_bf16_f32 v48, v52, v53
	v_cvt_pk_bf16_f32 v49, v54, v55
	s_waitcnt vmcnt(14)
	v_lshlrev_b32_e32 v52, 16, v142
	v_cvt_pk_bf16_f32 v50, v50, v51
	v_cvt_pk_bf16_f32 v51, v56, v57
	global_store_dwordx4 v[60:61], v[48:51], off offset:256
	v_and_b32_e32 v53, 0xffff0000, v142
	v_lshlrev_b32_e32 v54, 16, v143
	v_lshlrev_b32_e32 v48, 16, v140
	v_and_b32_e32 v49, 0xffff0000, v140
	v_and_b32_e32 v55, 0xffff0000, v143
	v_pk_fma_f32 v[44:45], v[44:45], v[212:213], v[48:49]
	v_lshlrev_b32_e32 v50, 16, v141
	v_and_b32_e32 v51, 0xffff0000, v141
	v_pk_fma_f32 v[48:49], v[42:43], v[210:211], v[54:55]
	v_pk_fma_f32 v[42:43], v[40:41], v[208:209], v[52:53]
	v_cvt_pk_bf16_f32 v40, v44, v45
	v_add_co_u32_e32 v44, vcc, s33, v144
	v_pk_fma_f32 v[46:47], v[46:47], v[214:215], v[50:51]
	s_nop 0
	v_addc_co_u32_e32 v45, vcc, 0, v145, vcc
	v_cvt_pk_bf16_f32 v41, v46, v47
	v_cvt_pk_bf16_f32 v42, v42, v43
	v_cvt_pk_bf16_f32 v43, v48, v49
	global_store_dwordx4 v[44:45], v[40:43], off
	s_waitcnt vmcnt(15)
	v_lshlrev_b32_e32 v46, 16, v138
	v_and_b32_e32 v47, 0xffff0000, v138
	v_lshlrev_b32_e32 v40, 16, v136
	v_and_b32_e32 v41, 0xffff0000, v136
	v_lshlrev_b32_e32 v42, 16, v137
	v_and_b32_e32 v43, 0xffff0000, v137
	v_lshlrev_b32_e32 v48, 16, v139
	v_and_b32_e32 v49, 0xffff0000, v139
	v_pk_fma_f32 v[38:39], v[38:39], v[206:207], v[42:43]
	v_pk_fma_f32 v[36:37], v[36:37], v[204:205], v[40:41]
	v_pk_fma_f32 v[40:41], v[34:35], v[202:203], v[48:49]
	v_pk_fma_f32 v[34:35], v[32:33], v[200:201], v[46:47]
	v_cvt_pk_bf16_f32 v32, v36, v37
	v_cvt_pk_bf16_f32 v33, v38, v39
	s_waitcnt vmcnt(14)
	v_lshlrev_b32_e32 v36, 16, v134
	v_cvt_pk_bf16_f32 v34, v34, v35
	v_cvt_pk_bf16_f32 v35, v40, v41
	global_store_dwordx4 v[44:45], v[32:35], off offset:256
	v_and_b32_e32 v37, 0xffff0000, v134
	v_lshlrev_b32_e32 v38, 16, v135
	v_lshlrev_b32_e32 v32, 16, v132
	v_and_b32_e32 v33, 0xffff0000, v132
	v_and_b32_e32 v39, 0xffff0000, v135
	v_pk_fma_f32 v[28:29], v[28:29], v[212:213], v[32:33]
	v_lshlrev_b32_e32 v34, 16, v133
	v_and_b32_e32 v35, 0xffff0000, v133
	v_pk_fma_f32 v[32:33], v[26:27], v[210:211], v[38:39]
	v_pk_fma_f32 v[26:27], v[24:25], v[208:209], v[36:37]
	v_cvt_pk_bf16_f32 v24, v28, v29
	v_add_co_u32_e32 v28, vcc, s18, v144
	v_pk_fma_f32 v[30:31], v[30:31], v[214:215], v[34:35]
	s_nop 0
	v_addc_co_u32_e32 v29, vcc, 0, v145, vcc
	v_cvt_pk_bf16_f32 v25, v30, v31
	v_cvt_pk_bf16_f32 v26, v26, v27
	v_cvt_pk_bf16_f32 v27, v32, v33
	global_store_dwordx4 v[28:29], v[24:27], off
	s_waitcnt vmcnt(15)
	v_lshlrev_b32_e32 v30, 16, v130
	v_and_b32_e32 v31, 0xffff0000, v130
	v_lshlrev_b32_e32 v24, 16, v128
	v_and_b32_e32 v25, 0xffff0000, v128
	v_lshlrev_b32_e32 v26, 16, v129
	v_and_b32_e32 v27, 0xffff0000, v129
	v_lshlrev_b32_e32 v32, 16, v131
	v_and_b32_e32 v33, 0xffff0000, v131
	v_pk_fma_f32 v[22:23], v[22:23], v[206:207], v[26:27]
	v_pk_fma_f32 v[20:21], v[20:21], v[204:205], v[24:25]
	v_pk_fma_f32 v[24:25], v[18:19], v[202:203], v[32:33]
	v_pk_fma_f32 v[18:19], v[16:17], v[200:201], v[30:31]
	v_cvt_pk_bf16_f32 v16, v20, v21
	v_cvt_pk_bf16_f32 v17, v22, v23
	s_waitcnt vmcnt(14)
	v_lshlrev_b32_e32 v20, 16, v126
	v_cvt_pk_bf16_f32 v18, v18, v19
	v_cvt_pk_bf16_f32 v19, v24, v25
	global_store_dwordx4 v[28:29], v[16:19], off offset:256
	v_and_b32_e32 v21, 0xffff0000, v126
	v_lshlrev_b32_e32 v22, 16, v127
	v_lshlrev_b32_e32 v16, 16, v124
	v_and_b32_e32 v17, 0xffff0000, v124
	v_and_b32_e32 v23, 0xffff0000, v127
	v_pk_fma_f32 v[12:13], v[12:13], v[212:213], v[16:17]
	v_lshlrev_b32_e32 v18, 16, v125
	v_and_b32_e32 v19, 0xffff0000, v125
	v_pk_fma_f32 v[16:17], v[10:11], v[210:211], v[22:23]
	v_pk_fma_f32 v[10:11], v[8:9], v[208:209], v[20:21]
	v_cvt_pk_bf16_f32 v8, v12, v13
	v_add_co_u32_e32 v12, vcc, s19, v144
	v_pk_fma_f32 v[14:15], v[14:15], v[214:215], v[18:19]
	s_nop 0
	v_addc_co_u32_e32 v13, vcc, 0, v145, vcc
	v_cvt_pk_bf16_f32 v9, v14, v15
	v_cvt_pk_bf16_f32 v10, v10, v11
	v_cvt_pk_bf16_f32 v11, v16, v17
	global_store_dwordx4 v[12:13], v[8:11], off
	s_waitcnt vmcnt(15)
	v_lshlrev_b32_e32 v14, 16, v122
	v_and_b32_e32 v15, 0xffff0000, v122
	v_lshlrev_b32_e32 v8, 16, v120
	v_and_b32_e32 v9, 0xffff0000, v120
	v_lshlrev_b32_e32 v16, 16, v123
	v_and_b32_e32 v17, 0xffff0000, v123
	v_lshlrev_b32_e32 v10, 16, v121
	v_and_b32_e32 v11, 0xffff0000, v121
	v_pk_fma_f32 v[4:5], v[4:5], v[204:205], v[8:9]
	v_pk_fma_f32 v[8:9], v[2:3], v[202:203], v[16:17]
	v_pk_fma_f32 v[2:3], v[0:1], v[200:201], v[14:15]
	s_and_b64 vcc, exec, s[4:5]
	v_pk_fma_f32 v[6:7], v[6:7], v[206:207], v[10:11]
	v_cvt_pk_bf16_f32 v0, v4, v5
	s_nop 0
	v_cvt_pk_bf16_f32 v1, v6, v7
	v_cvt_pk_bf16_f32 v2, v2, v3
	v_cvt_pk_bf16_f32 v3, v8, v9
	global_store_dwordx4 v[12:13], v[0:3], off offset:256
	s_cbranch_vccz .LBB0_849
	s_waitcnt vmcnt(0)
	s_cmpk_gt_u32 s21, 0xff
	v_readlane_b32 s38, v255, 44
	s_cbranch_scc1 .LBB0_864
	s_barrier
